# phase-1 H rows and transposed in-projection weights stored write-through (less dirty data for barrier 2's L2 writeback)
# speedup vs baseline: 1.0077x; 1.0025x over previous
.LBB0_105:
	s_lshl_b32 s4, s9, 6
	v_or_b32_e32 v2, s4, v13
	s_ashr_i32 s9, s8, 31
	v_lshl_add_u64 v[28:29], s[8:9], 2, v[10:11]
	v_or_b32_e32 v27, 2, v2
	v_mad_i64_i32 v[32:33], s[8:9], v27, s16, v[28:29]
	v_or_b32_e32 v27, 4, v2
	v_mad_i64_i32 v[34:35], s[8:9], v27, s16, v[28:29]
	v_or_b32_e32 v27, 6, v2
	v_mad_i64_i32 v[36:37], s[8:9], v27, s16, v[28:29]
	v_or_b32_e32 v27, 8, v2
	v_mad_i64_i32 v[38:39], s[8:9], v27, s16, v[28:29]
	v_or_b32_e32 v27, 10, v2
	v_mad_i64_i32 v[40:41], s[8:9], v27, s16, v[28:29]
	v_or_b32_e32 v27, 12, v2
	v_mad_i64_i32 v[30:31], s[8:9], v2, s16, v[28:29]
	v_mad_i64_i32 v[42:43], s[8:9], v27, s16, v[28:29]
	v_or_b32_e32 v27, 14, v2
	v_mad_i64_i32 v[44:45], s[8:9], v27, s16, v[28:29]
	global_load_dword v27, v[30:31], off nt
	global_load_dword v46, v[32:33], off nt
	global_load_dword v47, v[34:35], off nt
	global_load_dword v48, v[36:37], off nt
	global_load_dword v49, v[38:39], off nt
	global_load_dword v50, v[40:41], off nt
	global_load_dword v51, v[42:43], off nt
	global_load_dword v52, v[44:45], off nt
	v_or_b32_e32 v30, 16, v2
	v_mad_i64_i32 v[30:31], s[8:9], v30, s16, v[28:29]
	v_or_b32_e32 v32, 18, v2
	v_or_b32_e32 v34, 20, v2
	v_or_b32_e32 v36, 22, v2
	v_or_b32_e32 v38, 24, v2
	v_or_b32_e32 v40, 26, v2
	v_or_b32_e32 v42, 28, v2
	v_or_b32_e32 v44, 30, v2
	v_mad_i64_i32 v[32:33], s[8:9], v32, s16, v[28:29]
	v_mad_i64_i32 v[34:35], s[8:9], v34, s16, v[28:29]
	v_mad_i64_i32 v[36:37], s[8:9], v36, s16, v[28:29]
	v_mad_i64_i32 v[38:39], s[8:9], v38, s16, v[28:29]
	v_mad_i64_i32 v[40:41], s[8:9], v40, s16, v[28:29]
	v_mad_i64_i32 v[42:43], s[8:9], v42, s16, v[28:29]
	v_mad_i64_i32 v[44:45], s[8:9], v44, s16, v[28:29]
	global_load_dword v53, v[30:31], off nt
	global_load_dword v54, v[32:33], off nt
	global_load_dword v55, v[34:35], off nt
	global_load_dword v56, v[36:37], off nt
	global_load_dword v57, v[38:39], off nt
	global_load_dword v58, v[40:41], off nt
	global_load_dword v59, v[42:43], off nt
	global_load_dword v60, v[44:45], off nt
	v_or_b32_e32 v30, 32, v2
	v_mad_i64_i32 v[30:31], s[8:9], v30, s16, v[28:29]
	v_or_b32_e32 v32, 34, v2
	v_or_b32_e32 v34, 36, v2
	v_or_b32_e32 v36, 38, v2
	v_or_b32_e32 v38, 40, v2
	v_or_b32_e32 v40, 42, v2
	v_or_b32_e32 v42, 44, v2
	v_or_b32_e32 v44, 46, v2
	v_mad_i64_i32 v[32:33], s[8:9], v32, s16, v[28:29]
	v_mad_i64_i32 v[34:35], s[8:9], v34, s16, v[28:29]
	v_mad_i64_i32 v[36:37], s[8:9], v36, s16, v[28:29]
	v_mad_i64_i32 v[38:39], s[8:9], v38, s16, v[28:29]
	v_mad_i64_i32 v[40:41], s[8:9], v40, s16, v[28:29]
	v_mad_i64_i32 v[42:43], s[8:9], v42, s16, v[28:29]
	v_mad_i64_i32 v[44:45], s[8:9], v44, s16, v[28:29]
	global_load_dword v61, v[30:31], off nt
	global_load_dword v62, v[32:33], off nt
	global_load_dword v63, v[34:35], off nt
	global_load_dword v64, v[36:37], off nt
	global_load_dword v65, v[38:39], off nt
	global_load_dword v66, v[40:41], off nt
	global_load_dword v67, v[42:43], off nt
	global_load_dword v68, v[44:45], off nt
	v_or_b32_e32 v30, 48, v2
	v_mad_i64_i32 v[30:31], s[8:9], v30, s16, v[28:29]
	v_or_b32_e32 v32, 50, v2
	v_or_b32_e32 v34, 52, v2
	v_or_b32_e32 v36, 54, v2
	v_or_b32_e32 v38, 56, v2
	v_or_b32_e32 v40, 58, v2
	v_or_b32_e32 v42, 60, v2
	v_or_b32_e32 v2, 62, v2
	v_mad_i64_i32 v[32:33], s[8:9], v32, s16, v[28:29]
	v_mad_i64_i32 v[34:35], s[8:9], v34, s16, v[28:29]
	v_mad_i64_i32 v[36:37], s[8:9], v36, s16, v[28:29]
	v_mad_i64_i32 v[38:39], s[8:9], v38, s16, v[28:29]
	v_mad_i64_i32 v[40:41], s[8:9], v40, s16, v[28:29]
	v_mad_i64_i32 v[42:43], s[8:9], v42, s16, v[28:29]
	v_mad_i64_i32 v[28:29], s[8:9], v2, s16, v[28:29]
	global_load_dword v2, v[30:31], off nt
	global_load_dword v44, v[32:33], off nt
	global_load_dword v45, v[34:35], off nt
	global_load_dword v69, v[36:37], off nt
	global_load_dword v70, v[38:39], off nt
	global_load_dword v71, v[40:41], off nt
	global_load_dword v72, v[42:43], off nt
	global_load_dword v73, v[28:29], off nt
	s_waitcnt vmcnt(30)
	ds_write2_b32 v18, v27, v46 offset1:66
	s_waitcnt vmcnt(28)
	ds_write2_b32 v18, v47, v48 offset0:132 offset1:198
	s_waitcnt vmcnt(26)
	ds_write2_b32 v19, v49, v50 offset0:8 offset1:74
	s_waitcnt vmcnt(24)
	ds_write2_b32 v19, v51, v52 offset0:140 offset1:206
	s_waitcnt vmcnt(22)
	ds_write2_b32 v20, v53, v54 offset0:16 offset1:82
	s_waitcnt vmcnt(20)
	ds_write2_b32 v20, v55, v56 offset0:148 offset1:214
	s_waitcnt vmcnt(18)
	ds_write2_b32 v21, v57, v58 offset0:24 offset1:90
	s_waitcnt vmcnt(16)
	ds_write2_b32 v21, v59, v60 offset0:156 offset1:222
	s_waitcnt vmcnt(14)
	ds_write2_b32 v22, v61, v62 offset0:32 offset1:98
	s_waitcnt vmcnt(12)
	ds_write2_b32 v22, v63, v64 offset0:164 offset1:230
	s_waitcnt vmcnt(10)
	ds_write2_b32 v23, v65, v66 offset0:40 offset1:106
	s_waitcnt vmcnt(8)
	ds_write2_b32 v23, v67, v68 offset0:172 offset1:238
	s_waitcnt vmcnt(6)
	ds_write2_b32 v24, v2, v44 offset0:48 offset1:114
	s_waitcnt vmcnt(4)
	ds_write2_b32 v24, v45, v69 offset0:180 offset1:246
	s_waitcnt vmcnt(2)
	ds_write2_b32 v25, v70, v71 offset0:56 offset1:122
	s_waitcnt vmcnt(0)
	ds_write2_b32 v25, v72, v73 offset0:188 offset1:254
	s_waitcnt lgkmcnt(0)
	ds_read2_b32 v[32:33], v26 offset1:8
	ds_read2_b32 v[36:37], v26 offset0:33 offset1:41
	ds_read2_b32 v[38:39], v26 offset0:66 offset1:74
	ds_read2_b32 v[40:41], v26 offset0:99 offset1:107
	ds_read2_b32 v[42:43], v26 offset0:132 offset1:140
	s_waitcnt lgkmcnt(4)
	v_bfe_u32 v2, v32, 16, 1
	v_add3_u32 v2, v32, v2, s13
	s_waitcnt lgkmcnt(3)
	v_bfe_u32 v27, v36, 16, 1
	v_lshrrev_b32_e32 v2, 16, v2
	v_add3_u32 v27, v36, v27, s13
	ds_read2_b32 v[44:45], v26 offset0:165 offset1:173
	v_and_or_b32 v28, v27, s14, v2
	s_waitcnt lgkmcnt(3)
	v_bfe_u32 v2, v38, 16, 1
	v_add3_u32 v2, v38, v2, s13
	s_waitcnt lgkmcnt(2)
	v_bfe_u32 v27, v40, 16, 1
	ds_read2_b32 v[46:47], v26 offset0:198 offset1:206
	v_lshrrev_b32_e32 v2, 16, v2
	v_add3_u32 v27, v40, v27, s13
	ds_read2_b32 v[48:49], v26 offset0:231 offset1:239
	v_and_or_b32 v29, v27, s14, v2
	s_waitcnt lgkmcnt(3)
	v_bfe_u32 v2, v42, 16, 1
	v_add3_u32 v2, v42, v2, s13
	s_waitcnt lgkmcnt(2)
	v_bfe_u32 v27, v44, 16, 1
	v_lshrrev_b32_e32 v2, 16, v2
	v_add3_u32 v27, v44, v27, s13
	v_and_or_b32 v30, v27, s14, v2
	s_waitcnt lgkmcnt(1)
	v_bfe_u32 v2, v46, 16, 1
	v_add3_u32 v2, v46, v2, s13
	s_waitcnt lgkmcnt(0)
	v_bfe_u32 v27, v48, 16, 1
	s_add_i32 s2, s2, s7
	v_lshrrev_b32_e32 v2, 16, v2
	v_add3_u32 v27, v48, v27, s13
	v_add_u32_e32 v50, s2, v14
	s_ashr_i32 s5, s4, 31
	v_and_or_b32 v31, v27, s14, v2
	v_ashrrev_i32_e32 v51, 31, v50
	v_bfe_u32 v2, v33, 16, 1
	v_lshl_add_u64 v[34:35], s[4:5], 1, v[6:7]
	v_lshlrev_b64 v[52:53], 11, v[50:51]
	v_add3_u32 v2, v33, v2, s13
	v_bfe_u32 v27, v37, 16, 1
	v_lshl_add_u64 v[52:53], v[34:35], 0, v[52:53]
	v_lshrrev_b32_e32 v2, 16, v2
	v_add3_u32 v27, v37, v27, s13
	global_store_dwordx4 v[52:53], v[28:31], off sc1
	v_add_u32_e32 v32, 8, v50
	v_ashrrev_i32_e32 v33, 31, v32
	v_and_or_b32 v28, v27, s14, v2
	v_bfe_u32 v2, v39, 16, 1
	v_add3_u32 v2, v39, v2, s13
	v_bfe_u32 v27, v41, 16, 1
	v_lshrrev_b32_e32 v2, 16, v2
	v_add3_u32 v27, v41, v27, s13
	v_and_or_b32 v29, v27, s14, v2
	v_bfe_u32 v2, v43, 16, 1
	v_add3_u32 v2, v43, v2, s13
	v_bfe_u32 v27, v45, 16, 1
	v_lshrrev_b32_e32 v2, 16, v2
	v_add3_u32 v27, v45, v27, s13
	v_and_or_b32 v30, v27, s14, v2
	v_bfe_u32 v2, v47, 16, 1
	v_add3_u32 v2, v47, v2, s13
	v_bfe_u32 v27, v49, 16, 1
	v_lshrrev_b32_e32 v2, 16, v2
	v_add3_u32 v27, v49, v27, s13
	v_lshlrev_b64 v[32:33], 11, v[32:33]
	v_and_or_b32 v31, v27, s14, v2
	ds_read2_b32 v[36:37], v26 offset0:16 offset1:24
	v_lshl_add_u64 v[32:33], v[34:35], 0, v[32:33]
	global_store_dwordx4 v[32:33], v[28:31], off sc1
	ds_read2_b32 v[32:33], v26 offset0:49 offset1:57
	ds_read2_b32 v[38:39], v26 offset0:82 offset1:90
	ds_read2_b32 v[40:41], v26 offset0:115 offset1:123
	s_waitcnt lgkmcnt(3)
	v_bfe_u32 v2, v36, 16, 1
	v_add3_u32 v2, v36, v2, s13
	s_waitcnt lgkmcnt(2)
	v_bfe_u32 v27, v32, 16, 1
	ds_read2_b32 v[42:43], v26 offset0:148 offset1:156
	v_lshrrev_b32_e32 v2, 16, v2
	v_add3_u32 v27, v32, v27, s13
	ds_read2_b32 v[44:45], v26 offset0:181 offset1:189
	v_and_or_b32 v28, v27, s14, v2
	s_waitcnt lgkmcnt(3)
	v_bfe_u32 v2, v38, 16, 1
	v_add3_u32 v2, v38, v2, s13
	s_waitcnt lgkmcnt(2)
	v_bfe_u32 v27, v40, 16, 1
	ds_read2_b32 v[46:47], v26 offset0:214 offset1:222
	v_lshrrev_b32_e32 v2, 16, v2
	v_add3_u32 v27, v40, v27, s13
	ds_read2_b32 v[48:49], v26 offset0:247 offset1:255
	v_and_or_b32 v29, v27, s14, v2
	s_waitcnt lgkmcnt(3)
	v_bfe_u32 v2, v42, 16, 1
	v_add3_u32 v2, v42, v2, s13
	s_waitcnt lgkmcnt(2)
	v_bfe_u32 v27, v44, 16, 1
	v_lshrrev_b32_e32 v2, 16, v2
	v_add3_u32 v27, v44, v27, s13
	v_and_or_b32 v30, v27, s14, v2
	s_waitcnt lgkmcnt(1)
	v_bfe_u32 v2, v46, 16, 1
	v_add3_u32 v2, v46, v2, s13
	s_waitcnt lgkmcnt(0)
	v_bfe_u32 v27, v48, 16, 1
	v_lshrrev_b32_e32 v2, 16, v2
	v_add3_u32 v27, v48, v27, s13
	v_add_u32_e32 v52, 16, v50
	v_and_or_b32 v31, v27, s14, v2
	v_ashrrev_i32_e32 v53, 31, v52
	v_bfe_u32 v2, v37, 16, 1
	v_lshlrev_b64 v[52:53], 11, v[52:53]
	v_add3_u32 v2, v37, v2, s13
	v_bfe_u32 v27, v33, 16, 1
	v_lshl_add_u64 v[52:53], v[34:35], 0, v[52:53]
	v_lshrrev_b32_e32 v2, 16, v2
	v_add3_u32 v27, v33, v27, s13
	global_store_dwordx4 v[52:53], v[28:31], off sc1
	v_add_u32_e32 v32, 24, v50
	v_ashrrev_i32_e32 v33, 31, v32
	v_and_or_b32 v28, v27, s14, v2
	v_bfe_u32 v2, v39, 16, 1
	v_add3_u32 v2, v39, v2, s13
	v_bfe_u32 v27, v41, 16, 1
	v_lshrrev_b32_e32 v2, 16, v2
	v_add3_u32 v27, v41, v27, s13
	v_and_or_b32 v29, v27, s14, v2
	v_bfe_u32 v2, v43, 16, 1
	v_add3_u32 v2, v43, v2, s13
	v_bfe_u32 v27, v45, 16, 1
	v_lshrrev_b32_e32 v2, 16, v2
	v_add3_u32 v27, v45, v27, s13
	v_and_or_b32 v30, v27, s14, v2
	v_bfe_u32 v2, v47, 16, 1
	v_add3_u32 v2, v47, v2, s13
	v_bfe_u32 v27, v49, 16, 1
	v_lshrrev_b32_e32 v2, 16, v2
	v_add3_u32 v27, v49, v27, s13
	v_lshlrev_b64 v[32:33], 11, v[32:33]
	v_and_or_b32 v31, v27, s14, v2
	v_lshl_add_u64 v[32:33], v[34:35], 0, v[32:33]
	global_store_dwordx4 v[32:33], v[28:31], off sc1
	s_waitcnt lgkmcnt(0)

.LBB0_107:
	s_cmpk_gt_i32 s0, 0x7ff
	s_mov_b64 s[4:5], -1
	s_cbranch_scc0 .LBB0_109
	s_and_b32 s4, s7, 0x3e0
	s_and_b32 s5, s11, 0x1ffc0
	v_or_b32_e32 v2, s5, v13
	s_lshl_b32 s2, s4, 2
	v_lshl_add_u64 v[28:29], v[8:9], 0, s[2:3]
	v_lshlrev_b32_e32 v2, 12, v2
	v_lshl_add_u64 v[28:29], v[28:29], 0, v[2:3]
	v_add_co_u32_e32 v30, vcc, 0x2000, v28
	s_lshl_b32 s2, s5, 1
	s_nop 0
	v_addc_co_u32_e32 v31, vcc, 0, v29, vcc
	v_add_co_u32_e32 v32, vcc, 0x4000, v28
	s_nop 1
	v_addc_co_u32_e32 v33, vcc, 0, v29, vcc
	v_add_co_u32_e32 v34, vcc, 0x6000, v28
	s_nop 1
	v_addc_co_u32_e32 v35, vcc, 0, v29, vcc
	v_add_co_u32_e32 v36, vcc, 0x8000, v28
	s_nop 1
	v_addc_co_u32_e32 v37, vcc, 0, v29, vcc
	v_add_co_u32_e32 v38, vcc, 0xa000, v28
	s_nop 1
	v_addc_co_u32_e32 v39, vcc, 0, v29, vcc
	v_add_co_u32_e32 v40, vcc, 0xc000, v28
	s_nop 1
	v_addc_co_u32_e32 v41, vcc, 0, v29, vcc
	v_add_co_u32_e32 v42, vcc, 0xe000, v28
	s_nop 1
	v_addc_co_u32_e32 v43, vcc, 0, v29, vcc
	global_load_dword v2, v[28:29], off nt
	global_load_dword v27, v[30:31], off nt
	global_load_dword v46, v[32:33], off nt
	global_load_dword v47, v[34:35], off nt
	global_load_dword v48, v[36:37], off nt
	global_load_dword v49, v[38:39], off nt
	global_load_dword v50, v[40:41], off nt
	global_load_dword v51, v[42:43], off nt
	v_add_co_u32_e32 v30, vcc, 0x10000, v28
	s_nop 1
	v_addc_co_u32_e32 v31, vcc, 0, v29, vcc
	v_add_co_u32_e32 v32, vcc, 0x12000, v28
	s_nop 1
	v_addc_co_u32_e32 v33, vcc, 0, v29, vcc
	v_add_co_u32_e32 v34, vcc, 0x14000, v28
	s_nop 1
	v_addc_co_u32_e32 v35, vcc, 0, v29, vcc
	v_add_co_u32_e32 v36, vcc, 0x16000, v28
	s_nop 1
	v_addc_co_u32_e32 v37, vcc, 0, v29, vcc
	v_add_co_u32_e32 v38, vcc, 0x18000, v28
	s_nop 1
	v_addc_co_u32_e32 v39, vcc, 0, v29, vcc
	v_add_co_u32_e32 v40, vcc, 0x1a000, v28
	s_nop 1
	v_addc_co_u32_e32 v41, vcc, 0, v29, vcc
	v_add_co_u32_e32 v42, vcc, 0x1c000, v28
	s_nop 1
	v_addc_co_u32_e32 v43, vcc, 0, v29, vcc
	v_add_co_u32_e32 v44, vcc, 0x1e000, v28
	s_nop 1
	v_addc_co_u32_e32 v45, vcc, 0, v29, vcc
	global_load_dword v52, v[30:31], off nt
	global_load_dword v53, v[32:33], off nt
	global_load_dword v54, v[34:35], off nt
	global_load_dword v55, v[36:37], off nt
	global_load_dword v56, v[38:39], off nt
	global_load_dword v57, v[40:41], off nt
	global_load_dword v58, v[42:43], off nt
	global_load_dword v59, v[44:45], off nt
	v_add_co_u32_e32 v30, vcc, 0x20000, v28
	s_nop 1
	v_addc_co_u32_e32 v31, vcc, 0, v29, vcc
	v_add_co_u32_e32 v32, vcc, 0x22000, v28
	s_nop 1
	v_addc_co_u32_e32 v33, vcc, 0, v29, vcc
	v_add_co_u32_e32 v34, vcc, 0x24000, v28
	s_nop 1
	v_addc_co_u32_e32 v35, vcc, 0, v29, vcc
	v_add_co_u32_e32 v36, vcc, 0x26000, v28
	s_nop 1
	v_addc_co_u32_e32 v37, vcc, 0, v29, vcc
	v_add_co_u32_e32 v38, vcc, 0x28000, v28
	s_nop 1
	v_addc_co_u32_e32 v39, vcc, 0, v29, vcc
	v_add_co_u32_e32 v40, vcc, 0x2a000, v28
	s_nop 1
	v_addc_co_u32_e32 v41, vcc, 0, v29, vcc
	v_add_co_u32_e32 v42, vcc, 0x2c000, v28
	s_nop 1
	v_addc_co_u32_e32 v43, vcc, 0, v29, vcc
	v_add_co_u32_e32 v44, vcc, 0x2e000, v28
	s_nop 1
	v_addc_co_u32_e32 v45, vcc, 0, v29, vcc
	global_load_dword v60, v[30:31], off nt
	global_load_dword v61, v[32:33], off nt
	global_load_dword v62, v[34:35], off nt
	global_load_dword v63, v[36:37], off nt
	global_load_dword v64, v[38:39], off nt
	global_load_dword v65, v[40:41], off nt
	global_load_dword v66, v[42:43], off nt
	global_load_dword v67, v[44:45], off nt
	v_add_co_u32_e32 v30, vcc, 0x30000, v28
	s_nop 1
	v_addc_co_u32_e32 v31, vcc, 0, v29, vcc
	v_add_co_u32_e32 v32, vcc, 0x32000, v28
	s_nop 1
	v_addc_co_u32_e32 v33, vcc, 0, v29, vcc
	v_add_co_u32_e32 v34, vcc, 0x34000, v28
	s_nop 1
	v_addc_co_u32_e32 v35, vcc, 0, v29, vcc
	v_add_co_u32_e32 v36, vcc, 0x36000, v28
	s_nop 1
	v_addc_co_u32_e32 v37, vcc, 0, v29, vcc
	v_add_co_u32_e32 v38, vcc, 0x38000, v28
	s_nop 1
	v_addc_co_u32_e32 v39, vcc, 0, v29, vcc
	v_add_co_u32_e32 v40, vcc, 0x3a000, v28
	s_nop 1
	v_addc_co_u32_e32 v41, vcc, 0, v29, vcc
	v_add_co_u32_e32 v42, vcc, 0x3c000, v28
	s_nop 1
	v_addc_co_u32_e32 v43, vcc, 0, v29, vcc
	v_add_co_u32_e32 v28, vcc, 0x3e000, v28
	s_nop 1
	v_addc_co_u32_e32 v29, vcc, 0, v29, vcc
	global_load_dword v44, v[30:31], off nt
	global_load_dword v45, v[32:33], off nt
	global_load_dword v68, v[34:35], off nt
	global_load_dword v69, v[36:37], off nt
	global_load_dword v70, v[38:39], off nt
	global_load_dword v71, v[40:41], off nt
	global_load_dword v72, v[42:43], off nt
	global_load_dword v73, v[28:29], off nt
	s_waitcnt vmcnt(30)
	ds_write2_b32 v18, v2, v27 offset1:66
	s_waitcnt vmcnt(28)
	ds_write2_b32 v18, v46, v47 offset0:132 offset1:198
	s_waitcnt vmcnt(26)
	ds_write2_b32 v19, v48, v49 offset0:8 offset1:74
	s_waitcnt vmcnt(24)
	ds_write2_b32 v19, v50, v51 offset0:140 offset1:206
	s_waitcnt vmcnt(22)
	ds_write2_b32 v20, v52, v53 offset0:16 offset1:82
	s_waitcnt vmcnt(20)
	ds_write2_b32 v20, v54, v55 offset0:148 offset1:214
	s_waitcnt vmcnt(18)
	ds_write2_b32 v21, v56, v57 offset0:24 offset1:90
	s_waitcnt vmcnt(16)
	ds_write2_b32 v21, v58, v59 offset0:156 offset1:222
	s_waitcnt vmcnt(14)
	ds_write2_b32 v22, v60, v61 offset0:32 offset1:98
	s_waitcnt vmcnt(12)
	ds_write2_b32 v22, v62, v63 offset0:164 offset1:230
	s_waitcnt vmcnt(10)
	ds_write2_b32 v23, v64, v65 offset0:40 offset1:106
	s_waitcnt vmcnt(8)
	ds_write2_b32 v23, v66, v67 offset0:172 offset1:238
	s_waitcnt vmcnt(6)
	ds_write2_b32 v24, v44, v45 offset0:48 offset1:114
	s_waitcnt vmcnt(4)
	ds_write2_b32 v24, v68, v69 offset0:180 offset1:246
	s_waitcnt vmcnt(2)
	ds_write2_b32 v25, v70, v71 offset0:56 offset1:122
	s_waitcnt vmcnt(0)
	ds_write2_b32 v25, v72, v73 offset0:188 offset1:254
	s_waitcnt lgkmcnt(0)
	ds_read2_b32 v[32:33], v26 offset1:8
	ds_read2_b32 v[36:37], v26 offset0:33 offset1:41
	ds_read2_b32 v[38:39], v26 offset0:66 offset1:74
	ds_read2_b32 v[40:41], v26 offset0:99 offset1:107
	ds_read2_b32 v[42:43], v26 offset0:132 offset1:140
	s_waitcnt lgkmcnt(4)
	v_bfe_u32 v2, v32, 16, 1
	v_add3_u32 v2, v32, v2, s13
	s_waitcnt lgkmcnt(3)
	v_bfe_u32 v27, v36, 16, 1
	v_lshrrev_b32_e32 v2, 16, v2
	v_add3_u32 v27, v36, v27, s13
	ds_read2_b32 v[44:45], v26 offset0:165 offset1:173
	v_and_or_b32 v28, v27, s14, v2
	s_waitcnt lgkmcnt(3)
	v_bfe_u32 v2, v38, 16, 1
	v_add3_u32 v2, v38, v2, s13
	s_waitcnt lgkmcnt(2)
	v_bfe_u32 v27, v40, 16, 1
	ds_read2_b32 v[46:47], v26 offset0:198 offset1:206
	v_lshrrev_b32_e32 v2, 16, v2
	v_add3_u32 v27, v40, v27, s13
	ds_read2_b32 v[48:49], v26 offset0:231 offset1:239
	v_and_or_b32 v29, v27, s14, v2
	s_waitcnt lgkmcnt(3)
	v_bfe_u32 v2, v42, 16, 1
	v_add3_u32 v2, v42, v2, s13
	s_waitcnt lgkmcnt(2)
	v_bfe_u32 v27, v44, 16, 1
	v_lshrrev_b32_e32 v2, 16, v2
	v_add3_u32 v27, v44, v27, s13
	v_and_or_b32 v30, v27, s14, v2
	s_waitcnt lgkmcnt(1)
	v_bfe_u32 v2, v46, 16, 1
	v_add3_u32 v2, v46, v2, s13
	s_waitcnt lgkmcnt(0)
	v_bfe_u32 v27, v48, 16, 1
	v_lshrrev_b32_e32 v2, 16, v2
	v_add3_u32 v27, v48, v27, s13
	v_and_or_b32 v31, v27, s14, v2
	v_or_b32_e32 v2, s4, v14
	v_lshl_add_u64 v[34:35], v[4:5], 0, s[2:3]
	v_lshlrev_b32_e32 v2, 11, v2
	v_lshl_add_u64 v[50:51], v[34:35], 0, v[2:3]
	v_bfe_u32 v2, v33, 16, 1
	v_add3_u32 v2, v33, v2, s13
	v_bfe_u32 v27, v37, 16, 1
	v_lshrrev_b32_e32 v2, 16, v2
	v_add3_u32 v27, v37, v27, s13
	global_store_dwordx4 v[50:51], v[28:31], off sc1
	ds_read2_b32 v[32:33], v26 offset0:16 offset1:24
	s_nop 0
	v_and_or_b32 v28, v27, s14, v2
	v_bfe_u32 v2, v39, 16, 1
	v_add3_u32 v2, v39, v2, s13
	v_bfe_u32 v27, v41, 16, 1
	v_lshrrev_b32_e32 v2, 16, v2
	v_add3_u32 v27, v41, v27, s13
	v_and_or_b32 v29, v27, s14, v2
	v_bfe_u32 v2, v43, 16, 1
	v_add3_u32 v2, v43, v2, s13
	v_bfe_u32 v27, v45, 16, 1
	v_lshrrev_b32_e32 v2, 16, v2
	v_add3_u32 v27, v45, v27, s13
	v_and_or_b32 v30, v27, s14, v2
	v_bfe_u32 v2, v47, 16, 1
	v_add3_u32 v2, v47, v2, s13
	v_bfe_u32 v27, v49, 16, 1
	v_lshrrev_b32_e32 v2, 16, v2
	v_add3_u32 v27, v49, v27, s13
	v_and_or_b32 v31, v27, s14, v2
	v_or_b32_e32 v2, s4, v15
	v_lshlrev_b32_e32 v2, 11, v2
	v_lshl_add_u64 v[36:37], v[34:35], 0, v[2:3]
	global_store_dwordx4 v[36:37], v[28:31], off sc1
	ds_read2_b32 v[36:37], v26 offset0:49 offset1:57
	ds_read2_b32 v[38:39], v26 offset0:82 offset1:90
	ds_read2_b32 v[40:41], v26 offset0:115 offset1:123
	s_waitcnt lgkmcnt(3)
	v_bfe_u32 v2, v32, 16, 1
	v_add3_u32 v2, v32, v2, s13
	s_waitcnt lgkmcnt(2)
	v_bfe_u32 v27, v36, 16, 1
	ds_read2_b32 v[42:43], v26 offset0:148 offset1:156
	v_lshrrev_b32_e32 v2, 16, v2
	v_add3_u32 v27, v36, v27, s13
	ds_read2_b32 v[44:45], v26 offset0:181 offset1:189
	v_and_or_b32 v28, v27, s14, v2
	s_waitcnt lgkmcnt(3)
	v_bfe_u32 v2, v38, 16, 1
	v_add3_u32 v2, v38, v2, s13
	s_waitcnt lgkmcnt(2)
	v_bfe_u32 v27, v40, 16, 1
	ds_read2_b32 v[46:47], v26 offset0:214 offset1:222
	v_lshrrev_b32_e32 v2, 16, v2
	v_add3_u32 v27, v40, v27, s13
	ds_read2_b32 v[48:49], v26 offset0:247 offset1:255
	v_and_or_b32 v29, v27, s14, v2
	s_waitcnt lgkmcnt(3)
	v_bfe_u32 v2, v42, 16, 1
	v_add3_u32 v2, v42, v2, s13
	s_waitcnt lgkmcnt(2)
	v_bfe_u32 v27, v44, 16, 1
	v_lshrrev_b32_e32 v2, 16, v2
	v_add3_u32 v27, v44, v27, s13
	v_and_or_b32 v30, v27, s14, v2
	s_waitcnt lgkmcnt(1)
	v_bfe_u32 v2, v46, 16, 1
	v_add3_u32 v2, v46, v2, s13
	s_waitcnt lgkmcnt(0)
	v_bfe_u32 v27, v48, 16, 1
	v_lshrrev_b32_e32 v2, 16, v2
	v_add3_u32 v27, v48, v27, s13
	v_and_or_b32 v31, v27, s14, v2
	v_or_b32_e32 v2, s4, v16
	v_lshlrev_b32_e32 v2, 11, v2
	v_lshl_add_u64 v[50:51], v[34:35], 0, v[2:3]
	v_bfe_u32 v2, v33, 16, 1
	v_add3_u32 v2, v33, v2, s13
	v_bfe_u32 v27, v37, 16, 1
	v_lshrrev_b32_e32 v2, 16, v2
	v_add3_u32 v27, v37, v27, s13
	global_store_dwordx4 v[50:51], v[28:31], off sc1
	s_nop 1
	v_and_or_b32 v28, v27, s14, v2
	v_bfe_u32 v2, v39, 16, 1
	v_add3_u32 v2, v39, v2, s13
	v_bfe_u32 v27, v41, 16, 1
	v_lshrrev_b32_e32 v2, 16, v2
	v_add3_u32 v27, v41, v27, s13
	v_and_or_b32 v29, v27, s14, v2
	v_bfe_u32 v2, v43, 16, 1
	v_add3_u32 v2, v43, v2, s13
	v_bfe_u32 v27, v45, 16, 1
	v_lshrrev_b32_e32 v2, 16, v2
	v_add3_u32 v27, v45, v27, s13
	v_and_or_b32 v30, v27, s14, v2
	v_bfe_u32 v2, v47, 16, 1
	v_add3_u32 v2, v47, v2, s13
	v_bfe_u32 v27, v49, 16, 1
	v_lshrrev_b32_e32 v2, 16, v2
	v_add3_u32 v27, v49, v27, s13
	v_and_or_b32 v31, v27, s14, v2
	v_or_b32_e32 v2, s4, v17
	v_lshlrev_b32_e32 v2, 11, v2
	v_lshl_add_u64 v[32:33], v[34:35], 0, v[2:3]
	global_store_dwordx4 v[32:33], v[28:31], off sc1
	s_waitcnt lgkmcnt(0)
	s_mov_b64 s[4:5], 0

.LBB0_83:
	s_waitcnt vmcnt(3) lgkmcnt(7)
	v_pk_mul_f32 v[214:215], v[8:9], v[8:9]
	s_waitcnt lgkmcnt(6)
	v_pk_mul_f32 v[216:217], v[6:7], v[6:7]
	s_waitcnt vmcnt(0)
	v_mul_f32_e32 v213, v10, v10
	s_waitcnt lgkmcnt(5)
	v_pk_mov_b32 v[218:219], v[216:217], v[214:215] op_sel:[1,0]
	v_mov_b32_e32 v217, v215
	v_pk_add_f32 v[214:215], v[218:219], v[216:217]
	v_pk_mul_f32 v[216:217], v[4:5], v[4:5]
	v_pk_mul_f32 v[218:219], v[2:3], v[2:3]
	v_pk_add_f32 v[214:215], v[214:215], v[214:215] op_sel:[0,1] op_sel_hi:[1,0]
	s_waitcnt lgkmcnt(4)
	v_pk_mov_b32 v[220:221], v[218:219], v[216:217] op_sel:[1,0]
	v_mov_b32_e32 v219, v217
	v_pk_add_f32 v[216:217], v[220:221], v[218:219]
	v_mul_f32_e32 v218, v11, v11
	v_pk_add_f32 v[216:217], v[216:217], v[216:217] op_sel:[0,1] op_sel_hi:[1,0]
	v_mov_b32_e32 v215, v213
	v_mov_b32_e32 v217, v218
	v_pk_add_f32 v[214:215], v[214:215], v[216:217]
	v_mul_f32_e32 v216, v15, v15
	v_mul_f32_e32 v219, v12, v12
	v_pk_fma_f32 v[216:217], v[14:15], v[14:15], v[216:217] op_sel_hi:[1,1,0]
	v_mul_f32_e32 v218, v17, v17
	v_mul_f32_e32 v220, v13, v13
	v_mov_b32_e32 v217, v219
	v_pk_fma_f32 v[218:219], v[16:17], v[16:17], v[218:219] op_sel_hi:[1,1,0]
	s_add_i32 s20, s29, s35
	v_mov_b32_e32 v219, v220
	v_pk_add_f32 v[216:217], v[216:217], v[218:219]
	s_ashr_i32 s21, s20, 31
	v_pk_add_f32 v[214:215], v[214:215], v[216:217]
	s_lshl_b64 s[4:5], s[20:21], 11
	v_add_f32_e32 v213, v214, v215
	s_nop 1
	v_add_f32_dpp v213, v213, v213 quad_perm:[1,0,3,2] row_mask:0xf bank_mask:0xf bound_ctrl:1
	s_nop 1
	v_add_f32_dpp v213, v213, v213 quad_perm:[2,3,0,1] row_mask:0xf bank_mask:0xf bound_ctrl:1
	s_nop 1
	v_add_f32_dpp v213, v213, v213 row_half_mirror row_mask:0xf bank_mask:0xf bound_ctrl:1
	s_nop 1
	v_add_f32_dpp v213, v213, v213 row_mirror row_mask:0xf bank_mask:0xf bound_ctrl:1
	ds_bpermute_b32 v214, v200, v213
	s_waitcnt lgkmcnt(0)
	v_add_f32_e32 v213, v213, v214
	ds_bpermute_b32 v214, v203, v213
	s_waitcnt lgkmcnt(0)
	v_add_f32_e32 v213, v213, v214
	v_fmamk_f32 v213, v213, 0x3a800000, v211
	v_rsq_f32_e32 v230, v213
	ds_read_b128 v[214:217], v210
	ds_read_b128 v[218:221], v210 offset:4096
	ds_read_b128 v[222:225], v210 offset:1024
	ds_read_b128 v[226:229], v210 offset:5120
	v_pk_mul_f32 v[6:7], v[6:7], v[230:231] op_sel_hi:[1,0]
	v_pk_mul_f32 v[8:9], v[8:9], v[230:231] op_sel_hi:[1,0]
	s_waitcnt lgkmcnt(2)
	v_pk_fma_f32 v[6:7], v[214:215], v[6:7], v[218:219]
	v_pk_fma_f32 v[8:9], v[216:217], v[8:9], v[220:221]
	ds_read_b128 v[214:217], v210 offset:2048
	ds_read_b128 v[218:221], v210 offset:6144
	v_pk_mul_f32 v[2:3], v[2:3], v[230:231] op_sel_hi:[1,0]
	v_pk_mul_f32 v[4:5], v[4:5], v[230:231] op_sel_hi:[1,0]
	s_waitcnt lgkmcnt(2)
	v_pk_fma_f32 v[2:3], v[222:223], v[2:3], v[226:227]
	v_pk_fma_f32 v[4:5], v[224:225], v[4:5], v[228:229]
	ds_read_b128 v[222:225], v210 offset:3072
	ds_read_b128 v[226:229], v210 offset:7168
	v_pk_mul_f32 v[14:15], v[14:15], v[230:231] op_sel_hi:[1,0]
	v_pk_mul_f32 v[16:17], v[16:17], v[230:231] op_sel_hi:[1,0]
	s_waitcnt lgkmcnt(2)
	v_pk_fma_f32 v[14:15], v[214:215], v[14:15], v[218:219]
	v_pk_fma_f32 v[16:17], v[216:217], v[16:17], v[220:221]
	v_lshl_add_u64 v[214:215], v[206:207], 0, s[4:5]
	v_cvt_pk_bf16_f32 v216, v6, v7
	v_cvt_pk_bf16_f32 v217, v8, v9
	v_pk_mul_f32 v[10:11], v[10:11], v[230:231] op_sel_hi:[1,0]
	v_pk_mul_f32 v[12:13], v[12:13], v[230:231] op_sel_hi:[1,0]
	global_store_dwordx2 v[214:215], v[216:217], off
	v_cvt_pk_bf16_f32 v216, v2, v3
	v_cvt_pk_bf16_f32 v217, v4, v5
	s_waitcnt lgkmcnt(0)
	v_pk_fma_f32 v[12:13], v[224:225], v[12:13], v[228:229]
	v_pk_fma_f32 v[10:11], v[222:223], v[10:11], v[226:227]
	global_store_dwordx2 v[214:215], v[216:217], off offset:512
	v_cvt_pk_bf16_f32 v216, v14, v15
	v_cvt_pk_bf16_f32 v217, v16, v17
	global_store_dwordx2 v[214:215], v[216:217], off offset:1024
	v_cvt_pk_bf16_f32 v216, v10, v11
	v_cvt_pk_bf16_f32 v217, v12, v13
	global_store_dwordx2 v[214:215], v[216:217], off offset:1536
	v_fma_f32 v213, v6, v162, 0
	v_fma_f32 v214, v7, v163, 0
	v_fmac_f32_e32 v213, v8, v164
	v_fmac_f32_e32 v214, v9, v165
	v_fmac_f32_e32 v213, v2, v158
	v_fmac_f32_e32 v214, v3, v159
	v_fmac_f32_e32 v213, v4, v160
	v_fmac_f32_e32 v214, v5, v161
	v_fmac_f32_e32 v213, v14, v154
	v_fmac_f32_e32 v214, v15, v155
	v_fmac_f32_e32 v213, v16, v156
	v_fmac_f32_e32 v214, v17, v157
	v_fmac_f32_e32 v213, v10, v150
	v_fmac_f32_e32 v214, v11, v151
	v_fmac_f32_e32 v213, v12, v152
	v_fmac_f32_e32 v214, v13, v153
	v_add_f32_e32 v213, v214, v213
	v_fma_f32 v214, v6, v146, 0
	v_fma_f32 v215, v7, v147, 0
	v_fmac_f32_e32 v214, v8, v148
	v_fmac_f32_e32 v215, v9, v149
	v_fmac_f32_e32 v214, v2, v142
	v_fmac_f32_e32 v215, v3, v143
	v_fmac_f32_e32 v214, v4, v144
	v_fmac_f32_e32 v215, v5, v145
	v_fmac_f32_e32 v214, v14, v138
	v_fmac_f32_e32 v215, v15, v139
	v_fmac_f32_e32 v214, v16, v140
	v_fmac_f32_e32 v215, v17, v141
	v_fmac_f32_e32 v214, v10, v134
	v_fmac_f32_e32 v215, v11, v135
	v_fmac_f32_e32 v214, v12, v136
	v_fmac_f32_e32 v215, v13, v137
	v_add_f32_e32 v214, v215, v214
	v_fma_f32 v216, v7, v131, 0
	v_fmac_f32_e32 v216, v9, v133
	v_add_f32_dpp v214, v214, v214 quad_perm:[1,0,3,2] row_mask:0xf bank_mask:0xf bound_ctrl:1
	v_fmac_f32_e32 v216, v3, v127
	v_fmac_f32_e32 v216, v5, v129
	v_add_f32_dpp v214, v214, v214 quad_perm:[2,3,0,1] row_mask:0xf bank_mask:0xf bound_ctrl:1
	v_fmac_f32_e32 v216, v15, v123
	v_fmac_f32_e32 v216, v17, v125
	v_add_f32_dpp v214, v214, v214 row_half_mirror row_mask:0xf bank_mask:0xf bound_ctrl:1
	v_fmac_f32_e32 v216, v11, v119
	v_fmac_f32_e32 v216, v13, v121
	v_add_f32_dpp v215, v214, v214 row_mirror row_mask:0xf bank_mask:0xf bound_ctrl:1
	v_fma_f32 v214, v6, v130, 0
	v_fmac_f32_e32 v214, v8, v132
	v_fmac_f32_e32 v214, v2, v126
	v_fmac_f32_e32 v214, v4, v128
	v_fmac_f32_e32 v214, v14, v122
	v_fmac_f32_e32 v214, v16, v124
	v_fmac_f32_e32 v214, v10, v118
	v_fmac_f32_e32 v214, v12, v120
	v_add_f32_e32 v214, v216, v214
	v_fma_f32 v216, v7, v115, 0
	v_fmac_f32_e32 v216, v9, v117
	v_add_f32_dpp v214, v214, v214 quad_perm:[1,0,3,2] row_mask:0xf bank_mask:0xf bound_ctrl:1
	v_fmac_f32_e32 v216, v3, v111
	v_fmac_f32_e32 v216, v5, v113
	v_add_f32_dpp v214, v214, v214 quad_perm:[2,3,0,1] row_mask:0xf bank_mask:0xf bound_ctrl:1
	v_fmac_f32_e32 v216, v15, v107
	v_fmac_f32_e32 v216, v17, v109
	v_add_f32_dpp v214, v214, v214 row_half_mirror row_mask:0xf bank_mask:0xf bound_ctrl:1
	v_fmac_f32_e32 v216, v11, v103
	v_fmac_f32_e32 v216, v13, v105
	v_add_f32_dpp v217, v214, v214 row_mirror row_mask:0xf bank_mask:0xf bound_ctrl:1
	v_fma_f32 v214, v6, v114, 0
	v_fmac_f32_e32 v214, v8, v116
	v_fmac_f32_e32 v214, v2, v110
	v_fmac_f32_e32 v214, v4, v112
	v_fmac_f32_e32 v214, v14, v106
	v_fmac_f32_e32 v214, v16, v108
	v_fmac_f32_e32 v214, v10, v102
	v_fmac_f32_e32 v214, v12, v104
	v_add_f32_e32 v214, v216, v214
	v_fma_f32 v216, v7, v99, 0
	v_fmac_f32_e32 v216, v9, v101
	v_add_f32_dpp v214, v214, v214 quad_perm:[1,0,3,2] row_mask:0xf bank_mask:0xf bound_ctrl:1
	v_fmac_f32_e32 v216, v3, v95
	v_fmac_f32_e32 v216, v5, v97
	v_add_f32_dpp v214, v214, v214 quad_perm:[2,3,0,1] row_mask:0xf bank_mask:0xf bound_ctrl:1
	v_fmac_f32_e32 v216, v15, v91
	v_fmac_f32_e32 v216, v17, v93
	v_add_f32_dpp v214, v214, v214 row_half_mirror row_mask:0xf bank_mask:0xf bound_ctrl:1
	v_fmac_f32_e32 v216, v11, v87
	v_fmac_f32_e32 v216, v13, v89
	v_add_f32_dpp v219, v214, v214 row_mirror row_mask:0xf bank_mask:0xf bound_ctrl:1
	v_fma_f32 v214, v6, v98, 0
	v_fmac_f32_e32 v214, v8, v100
	v_fmac_f32_e32 v214, v2, v94
	v_fmac_f32_e32 v214, v4, v96
	v_fmac_f32_e32 v214, v14, v90
	v_fmac_f32_e32 v214, v16, v92
	v_fmac_f32_e32 v214, v10, v86
	v_fmac_f32_e32 v214, v12, v88
	v_add_f32_e32 v214, v216, v214
	v_fma_f32 v216, v7, v83, 0
	v_fmac_f32_e32 v216, v9, v85
	v_add_f32_dpp v214, v214, v214 quad_perm:[1,0,3,2] row_mask:0xf bank_mask:0xf bound_ctrl:1
	v_fmac_f32_e32 v216, v3, v79
	v_fmac_f32_e32 v216, v5, v81
	v_add_f32_dpp v214, v214, v214 quad_perm:[2,3,0,1] row_mask:0xf bank_mask:0xf bound_ctrl:1
	v_fmac_f32_e32 v216, v15, v75
	v_fmac_f32_e32 v216, v17, v77
	v_add_f32_dpp v214, v214, v214 row_half_mirror row_mask:0xf bank_mask:0xf bound_ctrl:1
	v_fmac_f32_e32 v216, v11, v71
	v_fmac_f32_e32 v216, v13, v73
	v_add_f32_dpp v221, v214, v214 row_mirror row_mask:0xf bank_mask:0xf bound_ctrl:1
	v_fma_f32 v214, v6, v82, 0
	v_fmac_f32_e32 v214, v8, v84
	v_fmac_f32_e32 v214, v2, v78
	v_fmac_f32_e32 v214, v4, v80
	v_fmac_f32_e32 v214, v14, v74
	v_fmac_f32_e32 v214, v16, v76
	v_fmac_f32_e32 v214, v10, v70
	v_fmac_f32_e32 v214, v12, v72
	v_add_f32_e32 v214, v216, v214
	v_fma_f32 v216, v7, v67, 0
	v_fmac_f32_e32 v216, v9, v69
	v_add_f32_dpp v214, v214, v214 quad_perm:[1,0,3,2] row_mask:0xf bank_mask:0xf bound_ctrl:1
	v_fmac_f32_e32 v216, v3, v63
	v_fmac_f32_e32 v216, v5, v65
	v_add_f32_dpp v214, v214, v214 quad_perm:[2,3,0,1] row_mask:0xf bank_mask:0xf bound_ctrl:1
	v_fmac_f32_e32 v216, v15, v59
	v_fmac_f32_e32 v216, v17, v61
	v_add_f32_dpp v214, v214, v214 row_half_mirror row_mask:0xf bank_mask:0xf bound_ctrl:1
	v_fmac_f32_e32 v216, v11, v55
	v_fmac_f32_e32 v216, v13, v57
	v_add_f32_dpp v223, v214, v214 row_mirror row_mask:0xf bank_mask:0xf bound_ctrl:1
	v_fma_f32 v214, v6, v66, 0
	v_fmac_f32_e32 v214, v8, v68
	v_fmac_f32_e32 v214, v2, v62
	v_fmac_f32_e32 v214, v4, v64
	v_fmac_f32_e32 v214, v14, v58
	v_fmac_f32_e32 v214, v16, v60
	v_fmac_f32_e32 v214, v10, v54
	v_fmac_f32_e32 v214, v12, v56
	v_add_f32_e32 v214, v216, v214
	v_fma_f32 v216, v7, v51, 0
	v_fmac_f32_e32 v216, v9, v53
	v_add_f32_dpp v214, v214, v214 quad_perm:[1,0,3,2] row_mask:0xf bank_mask:0xf bound_ctrl:1
	v_fmac_f32_e32 v216, v3, v47
	v_fmac_f32_e32 v216, v5, v49
	v_add_f32_dpp v214, v214, v214 quad_perm:[2,3,0,1] row_mask:0xf bank_mask:0xf bound_ctrl:1
	v_fmac_f32_e32 v216, v15, v43
	v_fmac_f32_e32 v216, v17, v45
	v_add_f32_dpp v214, v214, v214 row_half_mirror row_mask:0xf bank_mask:0xf bound_ctrl:1
	v_fmac_f32_e32 v216, v11, v39
	v_fmac_f32_e32 v216, v13, v41
	v_add_f32_dpp v225, v214, v214 row_mirror row_mask:0xf bank_mask:0xf bound_ctrl:1
	v_fma_f32 v214, v6, v50, 0
	v_fmac_f32_e32 v214, v8, v52
	v_fmac_f32_e32 v214, v2, v46
	v_fmac_f32_e32 v214, v4, v48
	v_fmac_f32_e32 v214, v14, v42
	v_fmac_f32_e32 v214, v16, v44
	v_fmac_f32_e32 v214, v10, v38
	v_fmac_f32_e32 v214, v12, v40
	v_add_f32_e32 v214, v216, v214
	v_add_f32_dpp v213, v213, v213 quad_perm:[1,0,3,2] row_mask:0xf bank_mask:0xf bound_ctrl:1
	ds_bpermute_b32 v218, v200, v215
	v_add_f32_dpp v214, v214, v214 quad_perm:[1,0,3,2] row_mask:0xf bank_mask:0xf bound_ctrl:1
	v_add_f32_dpp v213, v213, v213 quad_perm:[2,3,0,1] row_mask:0xf bank_mask:0xf bound_ctrl:1
	ds_bpermute_b32 v220, v200, v217
	v_add_f32_dpp v214, v214, v214 quad_perm:[2,3,0,1] row_mask:0xf bank_mask:0xf bound_ctrl:1
	v_add_f32_dpp v213, v213, v213 row_half_mirror row_mask:0xf bank_mask:0xf bound_ctrl:1
	ds_bpermute_b32 v222, v200, v219
	v_add_f32_dpp v214, v214, v214 row_half_mirror row_mask:0xf bank_mask:0xf bound_ctrl:1
	v_add_f32_dpp v213, v213, v213 row_mirror row_mask:0xf bank_mask:0xf bound_ctrl:1
	ds_bpermute_b32 v216, v200, v213
	v_add_f32_dpp v227, v214, v214 row_mirror row_mask:0xf bank_mask:0xf bound_ctrl:1
	ds_bpermute_b32 v224, v200, v221
	ds_bpermute_b32 v226, v200, v223
	ds_bpermute_b32 v228, v200, v225
	ds_bpermute_b32 v229, v200, v227
	s_waitcnt lgkmcnt(4)
	v_add_f32_e32 v213, v213, v216
	v_add_f32_e32 v215, v215, v218
	v_add_f32_e32 v217, v217, v220
	v_add_f32_e32 v219, v219, v222
	s_waitcnt lgkmcnt(3)
	v_add_f32_e32 v221, v221, v224
	s_waitcnt lgkmcnt(2)
	v_add_f32_e32 v223, v223, v226
	s_waitcnt lgkmcnt(1)
	v_add_f32_e32 v225, v225, v228
	s_waitcnt lgkmcnt(0)
	v_add_f32_e32 v227, v227, v229
	ds_bpermute_b32 v214, v203, v213
	ds_bpermute_b32 v216, v203, v215
	ds_bpermute_b32 v218, v203, v217
	ds_bpermute_b32 v220, v203, v219
	ds_bpermute_b32 v222, v203, v221
	ds_bpermute_b32 v224, v203, v223
	ds_bpermute_b32 v226, v203, v225
	ds_bpermute_b32 v228, v203, v227
	s_and_saveexec_b64 s[22:23], s[2:3]
	s_cbranch_execz .LBB0_85
	s_waitcnt lgkmcnt(0)
	v_add_f32_e32 v227, v227, v228
	v_add_f32_e32 v225, v225, v226
	s_waitcnt vmcnt(4)
	v_add_f32_e32 v226, v37, v227
	v_mul_f32_e64 v227, |v226|, s30
	v_exp_f32_e32 v227, v227
	v_add_f32_e32 v221, v221, v222
	v_add_f32_e32 v222, v219, v220
	v_add_f32_e32 v213, v213, v214
	v_add_f32_e32 v219, 1.0, v227
	v_cmp_gt_f32_e32 vcc, s31, v219
	v_add_f32_e32 v227, v215, v216
	v_add_f32_e32 v216, v36, v225
	v_cndmask_b32_e64 v220, 0, 32, vcc
	v_ldexp_f32 v219, v219, v220
	v_log_f32_e32 v219, v219
	v_mul_f32_e64 v215, |v216|, s30
	v_exp_f32_e32 v215, v215
	v_add_f32_e32 v223, v223, v224
	v_mul_f32_e32 v214, 0x3f317217, v219
	v_fma_f32 v214, v219, s33, -v214
	v_fmac_f32_e32 v214, 0x3377d1cf, v219
	v_fmac_f32_e32 v214, 0x3f317217, v219
	v_cmp_lt_f32_e64 s[4:5], |v219|, s34
	v_add_f32_e32 v215, 1.0, v215
	v_add_f32_e32 v224, v217, v218
	v_cndmask_b32_e64 v214, v219, v214, s[4:5]
	v_cmp_gt_f32_e64 s[4:5], s31, v215
	v_add_f32_e32 v220, v35, v223
	v_mul_f32_e64 v219, |v220|, s30
	v_cndmask_b32_e64 v217, 0, 32, s[4:5]
	v_ldexp_f32 v215, v215, v217
	v_log_f32_e32 v218, v215
	v_cndmask_b32_e32 v215, 0, v212, vcc
	v_sub_f32_e32 v215, v214, v215
	v_exp_f32_e32 v219, v219
	v_mul_f32_e32 v214, 0x3f317217, v218
	v_fma_f32 v214, v218, s33, -v214
	v_fmac_f32_e32 v214, 0x3377d1cf, v218
	v_fmac_f32_e32 v214, 0x3f317217, v218
	v_cmp_lt_f32_e64 vcc, |v218|, s34
	v_add_f32_e32 v223, v34, v221
	v_mul_f32_e64 v221, |v223|, s30
	v_cndmask_b32_e32 v214, v218, v214, vcc
	v_add_f32_e32 v218, 1.0, v219
	v_cmp_gt_f32_e32 vcc, s31, v218
	v_exp_f32_e32 v221, v221
	v_mul_f32_e32 v213, 0xbfb8aa3b, v213
	v_cndmask_b32_e64 v219, 0, 32, vcc
	v_ldexp_f32 v218, v218, v219
	v_log_f32_e32 v218, v218
	v_cndmask_b32_e64 v219, 0, v212, s[4:5]
	v_sub_f32_e32 v214, v214, v219
	v_exp_f32_e32 v213, v213
	v_mul_f32_e32 v219, 0x3f317217, v218
	v_fma_f32 v219, v218, s33, -v219
	v_fmac_f32_e32 v219, 0x3377d1cf, v218
	v_fmac_f32_e32 v219, 0x3f317217, v218
	v_cmp_lt_f32_e64 s[4:5], |v218|, s34
	v_mul_f32_e32 v222, 0xbfb8aa3b, v222
	v_max_f32_e32 v217, 0, v226
	v_cndmask_b32_e64 v218, v218, v219, s[4:5]
	v_add_f32_e32 v219, 1.0, v221
	v_cmp_gt_f32_e64 s[4:5], s31, v219
	v_max_f32_e32 v216, 0, v216
	v_exp_f32_e32 v222, v222
	v_cndmask_b32_e64 v221, 0, 32, s[4:5]
	v_ldexp_f32 v219, v219, v221
	v_log_f32_e32 v225, v219
	v_cndmask_b32_e32 v219, 0, v212, vcc
	v_sub_f32_e32 v219, v218, v219
	v_max_f32_e32 v221, 0, v220
	v_mul_f32_e32 v218, 0x3f317217, v225
	v_fma_f32 v218, v225, s33, -v218
	v_fmac_f32_e32 v218, 0x3377d1cf, v225
	v_fmac_f32_e32 v218, 0x3f317217, v225
	v_cmp_lt_f32_e64 vcc, |v225|, s34
	v_cndmask_b32_e64 v220, 0, v212, s[4:5]
	v_pk_add_f32 v[214:215], v[216:217], v[214:215]
	v_cndmask_b32_e32 v218, v225, v218, vcc
	v_sub_f32_e32 v218, v218, v220
	v_max_f32_e32 v220, 0, v223
	v_mul_f32_e32 v223, 0xbfb8aa3b, v224
	v_mul_f32_e32 v224, 0xbfb8aa3b, v227
	v_exp_f32_e32 v224, v224
	v_exp_f32_e32 v223, v223
	v_pk_add_f32 v[218:219], v[220:221], v[218:219]
	v_add_f32_e32 v213, 1.0, v213
	v_pk_mul_f32 v[216:217], v[214:215], s[10:11]
	v_pk_mul_f32 v[214:215], v[218:219], s[8:9] neg_lo:[0,1] neg_hi:[0,1]
	v_rcp_f32_e32 v218, v213
	v_add_f32_e32 v213, 1.0, v224
	v_rcp_f32_e32 v219, v213
	v_add_f32_e32 v213, 1.0, v223
	v_rcp_f32_e32 v220, v213
	v_add_f32_e32 v213, 1.0, v222
	s_lshl_b64 s[4:5], s[20:21], 4
	v_rcp_f32_e32 v221, v213
	s_add_u32 s20, s24, s4
	s_addc_u32 s21, s25, s5
	s_add_u32 s4, s26, s4
	s_addc_u32 s5, s27, s5
	global_store_dwordx4 v201, v[218:221], s[20:21] sc1
	global_store_dwordx4 v201, v[214:217], s[4:5] sc1

.LBB0_90:
	s_waitcnt lgkmcnt(7)
	v_pk_mul_f32 v[214:215], v[24:25], v[24:25]
	s_waitcnt lgkmcnt(6)
	v_pk_mul_f32 v[216:217], v[22:23], v[22:23]
	v_mul_f32_e32 v213, v26, v26
	s_waitcnt lgkmcnt(5)
	v_pk_mov_b32 v[218:219], v[216:217], v[214:215] op_sel:[1,0]
	v_mov_b32_e32 v217, v215
	v_pk_add_f32 v[214:215], v[218:219], v[216:217]
	v_pk_mul_f32 v[216:217], v[20:21], v[20:21]
	v_pk_mul_f32 v[218:219], v[18:19], v[18:19]
	v_pk_add_f32 v[214:215], v[214:215], v[214:215] op_sel:[0,1] op_sel_hi:[1,0]
	s_waitcnt lgkmcnt(4)
	v_pk_mov_b32 v[220:221], v[218:219], v[216:217] op_sel:[1,0]
	v_mov_b32_e32 v219, v217
	v_pk_add_f32 v[216:217], v[220:221], v[218:219]
	v_mul_f32_e32 v218, v27, v27
	v_pk_add_f32 v[216:217], v[216:217], v[216:217] op_sel:[0,1] op_sel_hi:[1,0]
	v_mov_b32_e32 v215, v213
	v_mov_b32_e32 v217, v218
	v_pk_add_f32 v[214:215], v[214:215], v[216:217]
	v_mul_f32_e32 v216, v31, v31
	v_mul_f32_e32 v219, v28, v28
	v_pk_fma_f32 v[216:217], v[30:31], v[30:31], v[216:217] op_sel_hi:[1,1,0]
	v_mul_f32_e32 v218, v33, v33
	v_mul_f32_e32 v220, v29, v29
	v_mov_b32_e32 v217, v219
	v_pk_fma_f32 v[218:219], v[32:33], v[32:33], v[218:219] op_sel_hi:[1,1,0]
	s_ashr_i32 s21, s20, 31
	v_mov_b32_e32 v219, v220
	v_pk_add_f32 v[216:217], v[216:217], v[218:219]
	s_lshl_b64 s[4:5], s[20:21], 11
	v_pk_add_f32 v[214:215], v[214:215], v[216:217]
	s_nop 0
	v_add_f32_e32 v213, v214, v215
	s_nop 1
	v_add_f32_dpp v213, v213, v213 quad_perm:[1,0,3,2] row_mask:0xf bank_mask:0xf bound_ctrl:1
	s_nop 1
	v_add_f32_dpp v213, v213, v213 quad_perm:[2,3,0,1] row_mask:0xf bank_mask:0xf bound_ctrl:1
	s_nop 1
	v_add_f32_dpp v213, v213, v213 row_half_mirror row_mask:0xf bank_mask:0xf bound_ctrl:1
	s_nop 1
	v_add_f32_dpp v213, v213, v213 row_mirror row_mask:0xf bank_mask:0xf bound_ctrl:1
	ds_bpermute_b32 v214, v200, v213
	s_waitcnt lgkmcnt(0)
	v_add_f32_e32 v213, v213, v214
	ds_bpermute_b32 v214, v203, v213
	s_waitcnt lgkmcnt(0)
	v_add_f32_e32 v213, v213, v214
	v_fmamk_f32 v213, v213, 0x3a800000, v211
	v_rsq_f32_e32 v230, v213
	ds_read_b128 v[214:217], v210
	ds_read_b128 v[218:221], v210 offset:4096
	ds_read_b128 v[222:225], v210 offset:1024
	ds_read_b128 v[226:229], v210 offset:5120
	v_pk_mul_f32 v[22:23], v[22:23], v[230:231] op_sel_hi:[1,0]
	v_pk_mul_f32 v[24:25], v[24:25], v[230:231] op_sel_hi:[1,0]
	s_waitcnt lgkmcnt(2)
	v_pk_fma_f32 v[22:23], v[214:215], v[22:23], v[218:219]
	v_pk_fma_f32 v[24:25], v[216:217], v[24:25], v[220:221]
	ds_read_b128 v[214:217], v210 offset:2048
	ds_read_b128 v[218:221], v210 offset:6144
	v_pk_mul_f32 v[18:19], v[18:19], v[230:231] op_sel_hi:[1,0]
	v_pk_mul_f32 v[20:21], v[20:21], v[230:231] op_sel_hi:[1,0]
	s_waitcnt lgkmcnt(2)
	v_pk_fma_f32 v[18:19], v[222:223], v[18:19], v[226:227]
	v_pk_fma_f32 v[20:21], v[224:225], v[20:21], v[228:229]
	ds_read_b128 v[222:225], v210 offset:3072
	ds_read_b128 v[226:229], v210 offset:7168
	v_pk_mul_f32 v[30:31], v[30:31], v[230:231] op_sel_hi:[1,0]
	v_pk_mul_f32 v[32:33], v[32:33], v[230:231] op_sel_hi:[1,0]
	s_waitcnt lgkmcnt(2)
	v_pk_fma_f32 v[30:31], v[214:215], v[30:31], v[218:219]
	v_pk_fma_f32 v[32:33], v[216:217], v[32:33], v[220:221]
	v_lshl_add_u64 v[214:215], v[206:207], 0, s[4:5]
	v_cvt_pk_bf16_f32 v216, v22, v23
	v_cvt_pk_bf16_f32 v217, v24, v25
	v_pk_mul_f32 v[26:27], v[26:27], v[230:231] op_sel_hi:[1,0]
	v_pk_mul_f32 v[28:29], v[28:29], v[230:231] op_sel_hi:[1,0]
	global_store_dwordx2 v[214:215], v[216:217], off
	v_cvt_pk_bf16_f32 v216, v18, v19
	v_cvt_pk_bf16_f32 v217, v20, v21
	s_waitcnt lgkmcnt(0)
	v_pk_fma_f32 v[28:29], v[224:225], v[28:29], v[228:229]
	v_pk_fma_f32 v[26:27], v[222:223], v[26:27], v[226:227]
	global_store_dwordx2 v[214:215], v[216:217], off offset:512
	v_cvt_pk_bf16_f32 v216, v30, v31
	v_cvt_pk_bf16_f32 v217, v32, v33
	global_store_dwordx2 v[214:215], v[216:217], off offset:1024
	v_cvt_pk_bf16_f32 v216, v26, v27
	v_cvt_pk_bf16_f32 v217, v28, v29
	global_store_dwordx2 v[214:215], v[216:217], off offset:1536
	v_fma_f32 v213, v22, v162, 0
	v_fma_f32 v214, v23, v163, 0
	v_fmac_f32_e32 v213, v24, v164
	v_fmac_f32_e32 v214, v25, v165
	v_fmac_f32_e32 v213, v18, v158
	v_fmac_f32_e32 v214, v19, v159
	v_fmac_f32_e32 v213, v20, v160
	v_fmac_f32_e32 v214, v21, v161
	v_fmac_f32_e32 v213, v30, v154
	v_fmac_f32_e32 v214, v31, v155
	v_fmac_f32_e32 v213, v32, v156
	v_fmac_f32_e32 v214, v33, v157
	v_fmac_f32_e32 v213, v26, v150
	v_fmac_f32_e32 v214, v27, v151
	v_fmac_f32_e32 v213, v28, v152
	v_fmac_f32_e32 v214, v29, v153
	v_add_f32_e32 v213, v214, v213
	v_fma_f32 v214, v22, v146, 0
	v_fma_f32 v215, v23, v147, 0
	v_fmac_f32_e32 v214, v24, v148
	v_fmac_f32_e32 v215, v25, v149
	v_fmac_f32_e32 v214, v18, v142
	v_fmac_f32_e32 v215, v19, v143
	v_fmac_f32_e32 v214, v20, v144
	v_fmac_f32_e32 v215, v21, v145
	v_fmac_f32_e32 v214, v30, v138
	v_fmac_f32_e32 v215, v31, v139
	v_fmac_f32_e32 v214, v32, v140
	v_fmac_f32_e32 v215, v33, v141
	v_fmac_f32_e32 v214, v26, v134
	v_fmac_f32_e32 v215, v27, v135
	v_fmac_f32_e32 v214, v28, v136
	v_fmac_f32_e32 v215, v29, v137
	v_add_f32_e32 v214, v215, v214
	v_fma_f32 v216, v23, v131, 0
	v_fmac_f32_e32 v216, v25, v133
	v_add_f32_dpp v214, v214, v214 quad_perm:[1,0,3,2] row_mask:0xf bank_mask:0xf bound_ctrl:1
	v_fmac_f32_e32 v216, v19, v127
	v_fmac_f32_e32 v216, v21, v129
	v_add_f32_dpp v214, v214, v214 quad_perm:[2,3,0,1] row_mask:0xf bank_mask:0xf bound_ctrl:1
	v_fmac_f32_e32 v216, v31, v123
	v_fmac_f32_e32 v216, v33, v125
	v_add_f32_dpp v214, v214, v214 row_half_mirror row_mask:0xf bank_mask:0xf bound_ctrl:1
	v_fmac_f32_e32 v216, v27, v119
	v_fmac_f32_e32 v216, v29, v121
	v_add_f32_dpp v215, v214, v214 row_mirror row_mask:0xf bank_mask:0xf bound_ctrl:1
	v_fma_f32 v214, v22, v130, 0
	v_fmac_f32_e32 v214, v24, v132
	v_fmac_f32_e32 v214, v18, v126
	v_fmac_f32_e32 v214, v20, v128
	v_fmac_f32_e32 v214, v30, v122
	v_fmac_f32_e32 v214, v32, v124
	v_fmac_f32_e32 v214, v26, v118
	v_fmac_f32_e32 v214, v28, v120
	v_add_f32_e32 v214, v216, v214
	v_fma_f32 v216, v23, v115, 0
	v_fmac_f32_e32 v216, v25, v117
	v_add_f32_dpp v214, v214, v214 quad_perm:[1,0,3,2] row_mask:0xf bank_mask:0xf bound_ctrl:1
	v_fmac_f32_e32 v216, v19, v111
	v_fmac_f32_e32 v216, v21, v113
	v_add_f32_dpp v214, v214, v214 quad_perm:[2,3,0,1] row_mask:0xf bank_mask:0xf bound_ctrl:1
	v_fmac_f32_e32 v216, v31, v107
	v_fmac_f32_e32 v216, v33, v109
	v_add_f32_dpp v214, v214, v214 row_half_mirror row_mask:0xf bank_mask:0xf bound_ctrl:1
	v_fmac_f32_e32 v216, v27, v103
	v_fmac_f32_e32 v216, v29, v105
	v_add_f32_dpp v217, v214, v214 row_mirror row_mask:0xf bank_mask:0xf bound_ctrl:1
	v_fma_f32 v214, v22, v114, 0
	v_fmac_f32_e32 v214, v24, v116
	v_fmac_f32_e32 v214, v18, v110
	v_fmac_f32_e32 v214, v20, v112
	v_fmac_f32_e32 v214, v30, v106
	v_fmac_f32_e32 v214, v32, v108
	v_fmac_f32_e32 v214, v26, v102
	v_fmac_f32_e32 v214, v28, v104
	v_add_f32_e32 v214, v216, v214
	v_fma_f32 v216, v23, v99, 0
	v_fmac_f32_e32 v216, v25, v101
	v_add_f32_dpp v214, v214, v214 quad_perm:[1,0,3,2] row_mask:0xf bank_mask:0xf bound_ctrl:1
	v_fmac_f32_e32 v216, v19, v95
	v_fmac_f32_e32 v216, v21, v97
	v_add_f32_dpp v214, v214, v214 quad_perm:[2,3,0,1] row_mask:0xf bank_mask:0xf bound_ctrl:1
	v_fmac_f32_e32 v216, v31, v91
	v_fmac_f32_e32 v216, v33, v93
	v_add_f32_dpp v214, v214, v214 row_half_mirror row_mask:0xf bank_mask:0xf bound_ctrl:1
	v_fmac_f32_e32 v216, v27, v87
	v_fmac_f32_e32 v216, v29, v89
	v_add_f32_dpp v219, v214, v214 row_mirror row_mask:0xf bank_mask:0xf bound_ctrl:1
	v_fma_f32 v214, v22, v98, 0
	v_fmac_f32_e32 v214, v24, v100
	v_fmac_f32_e32 v214, v18, v94
	v_fmac_f32_e32 v214, v20, v96
	v_fmac_f32_e32 v214, v30, v90
	v_fmac_f32_e32 v214, v32, v92
	v_fmac_f32_e32 v214, v26, v86
	v_fmac_f32_e32 v214, v28, v88
	v_add_f32_e32 v214, v216, v214
	v_fma_f32 v216, v23, v83, 0
	v_fmac_f32_e32 v216, v25, v85
	v_add_f32_dpp v214, v214, v214 quad_perm:[1,0,3,2] row_mask:0xf bank_mask:0xf bound_ctrl:1
	v_fmac_f32_e32 v216, v19, v79
	v_fmac_f32_e32 v216, v21, v81
	v_add_f32_dpp v214, v214, v214 quad_perm:[2,3,0,1] row_mask:0xf bank_mask:0xf bound_ctrl:1
	v_fmac_f32_e32 v216, v31, v75
	v_fmac_f32_e32 v216, v33, v77
	v_add_f32_dpp v214, v214, v214 row_half_mirror row_mask:0xf bank_mask:0xf bound_ctrl:1
	v_fmac_f32_e32 v216, v27, v71
	v_fmac_f32_e32 v216, v29, v73
	v_add_f32_dpp v221, v214, v214 row_mirror row_mask:0xf bank_mask:0xf bound_ctrl:1
	v_fma_f32 v214, v22, v82, 0
	v_fmac_f32_e32 v214, v24, v84
	v_fmac_f32_e32 v214, v18, v78
	v_fmac_f32_e32 v214, v20, v80
	v_fmac_f32_e32 v214, v30, v74
	v_fmac_f32_e32 v214, v32, v76
	v_fmac_f32_e32 v214, v26, v70
	v_fmac_f32_e32 v214, v28, v72
	v_add_f32_e32 v214, v216, v214
	v_fma_f32 v216, v23, v67, 0
	v_fmac_f32_e32 v216, v25, v69
	v_add_f32_dpp v214, v214, v214 quad_perm:[1,0,3,2] row_mask:0xf bank_mask:0xf bound_ctrl:1
	v_fmac_f32_e32 v216, v19, v63
	v_fmac_f32_e32 v216, v21, v65
	v_add_f32_dpp v214, v214, v214 quad_perm:[2,3,0,1] row_mask:0xf bank_mask:0xf bound_ctrl:1
	v_fmac_f32_e32 v216, v31, v59
	v_fmac_f32_e32 v216, v33, v61
	v_add_f32_dpp v214, v214, v214 row_half_mirror row_mask:0xf bank_mask:0xf bound_ctrl:1
	v_fmac_f32_e32 v216, v27, v55
	v_fmac_f32_e32 v216, v29, v57
	v_add_f32_dpp v223, v214, v214 row_mirror row_mask:0xf bank_mask:0xf bound_ctrl:1
	v_fma_f32 v214, v22, v66, 0
	v_fmac_f32_e32 v214, v24, v68
	v_fmac_f32_e32 v214, v18, v62
	v_fmac_f32_e32 v214, v20, v64
	v_fmac_f32_e32 v214, v30, v58
	v_fmac_f32_e32 v214, v32, v60
	v_fmac_f32_e32 v214, v26, v54
	v_fmac_f32_e32 v214, v28, v56
	v_add_f32_e32 v214, v216, v214
	v_fma_f32 v216, v23, v51, 0
	v_fmac_f32_e32 v216, v25, v53
	v_add_f32_dpp v214, v214, v214 quad_perm:[1,0,3,2] row_mask:0xf bank_mask:0xf bound_ctrl:1
	v_fmac_f32_e32 v216, v19, v47
	v_fmac_f32_e32 v216, v21, v49
	v_add_f32_dpp v214, v214, v214 quad_perm:[2,3,0,1] row_mask:0xf bank_mask:0xf bound_ctrl:1
	v_fmac_f32_e32 v216, v31, v43
	v_fmac_f32_e32 v216, v33, v45
	v_add_f32_dpp v214, v214, v214 row_half_mirror row_mask:0xf bank_mask:0xf bound_ctrl:1
	v_fmac_f32_e32 v216, v27, v39
	v_fmac_f32_e32 v216, v29, v41
	v_add_f32_dpp v225, v214, v214 row_mirror row_mask:0xf bank_mask:0xf bound_ctrl:1
	v_fma_f32 v214, v22, v50, 0
	v_fmac_f32_e32 v214, v24, v52
	v_fmac_f32_e32 v214, v18, v46
	v_fmac_f32_e32 v214, v20, v48
	v_fmac_f32_e32 v214, v30, v42
	v_fmac_f32_e32 v214, v32, v44
	v_fmac_f32_e32 v214, v26, v38
	v_fmac_f32_e32 v214, v28, v40
	v_add_f32_e32 v214, v216, v214
	v_add_f32_dpp v213, v213, v213 quad_perm:[1,0,3,2] row_mask:0xf bank_mask:0xf bound_ctrl:1
	ds_bpermute_b32 v218, v200, v215
	v_add_f32_dpp v214, v214, v214 quad_perm:[1,0,3,2] row_mask:0xf bank_mask:0xf bound_ctrl:1
	v_add_f32_dpp v213, v213, v213 quad_perm:[2,3,0,1] row_mask:0xf bank_mask:0xf bound_ctrl:1
	ds_bpermute_b32 v220, v200, v217
	v_add_f32_dpp v214, v214, v214 quad_perm:[2,3,0,1] row_mask:0xf bank_mask:0xf bound_ctrl:1
	v_add_f32_dpp v213, v213, v213 row_half_mirror row_mask:0xf bank_mask:0xf bound_ctrl:1
	ds_bpermute_b32 v222, v200, v219
	v_add_f32_dpp v214, v214, v214 row_half_mirror row_mask:0xf bank_mask:0xf bound_ctrl:1
	v_add_f32_dpp v213, v213, v213 row_mirror row_mask:0xf bank_mask:0xf bound_ctrl:1
	ds_bpermute_b32 v216, v200, v213
	v_add_f32_dpp v227, v214, v214 row_mirror row_mask:0xf bank_mask:0xf bound_ctrl:1
	ds_bpermute_b32 v224, v200, v221
	ds_bpermute_b32 v226, v200, v223
	ds_bpermute_b32 v228, v200, v225
	ds_bpermute_b32 v229, v200, v227
	s_waitcnt lgkmcnt(4)
	v_add_f32_e32 v213, v213, v216
	v_add_f32_e32 v215, v215, v218
	v_add_f32_e32 v217, v217, v220
	v_add_f32_e32 v219, v219, v222
	s_waitcnt lgkmcnt(3)
	v_add_f32_e32 v221, v221, v224
	s_waitcnt lgkmcnt(2)
	v_add_f32_e32 v223, v223, v226
	s_waitcnt lgkmcnt(1)
	v_add_f32_e32 v225, v225, v228
	s_waitcnt lgkmcnt(0)
	v_add_f32_e32 v227, v227, v229
	ds_bpermute_b32 v214, v203, v213
	ds_bpermute_b32 v216, v203, v215
	ds_bpermute_b32 v218, v203, v217
	ds_bpermute_b32 v220, v203, v219
	ds_bpermute_b32 v222, v203, v221
	ds_bpermute_b32 v224, v203, v223
	ds_bpermute_b32 v226, v203, v225
	ds_bpermute_b32 v228, v203, v227
	s_and_saveexec_b64 s[22:23], s[2:3]
	s_cbranch_execz .LBB0_92
	s_waitcnt lgkmcnt(0)
	v_add_f32_e32 v227, v227, v228
	v_add_f32_e32 v225, v225, v226
	s_waitcnt vmcnt(8)
	v_add_f32_e32 v226, v37, v227
	v_mul_f32_e64 v227, |v226|, s30
	v_exp_f32_e32 v227, v227
	v_add_f32_e32 v221, v221, v222
	v_add_f32_e32 v222, v219, v220
	v_add_f32_e32 v213, v213, v214
	v_add_f32_e32 v219, 1.0, v227
	v_cmp_gt_f32_e32 vcc, s31, v219
	v_add_f32_e32 v227, v215, v216
	v_add_f32_e32 v216, v36, v225
	v_cndmask_b32_e64 v220, 0, 32, vcc
	v_ldexp_f32 v219, v219, v220
	v_log_f32_e32 v219, v219
	v_mul_f32_e64 v215, |v216|, s30
	v_exp_f32_e32 v215, v215
	v_add_f32_e32 v223, v223, v224
	v_mul_f32_e32 v214, 0x3f317217, v219
	v_fma_f32 v214, v219, s33, -v214
	v_fmac_f32_e32 v214, 0x3377d1cf, v219
	v_fmac_f32_e32 v214, 0x3f317217, v219
	v_cmp_lt_f32_e64 s[4:5], |v219|, s34
	v_add_f32_e32 v215, 1.0, v215
	v_add_f32_e32 v224, v217, v218
	v_cndmask_b32_e64 v214, v219, v214, s[4:5]
	v_cmp_gt_f32_e64 s[4:5], s31, v215
	v_add_f32_e32 v220, v35, v223
	v_mul_f32_e64 v219, |v220|, s30
	v_cndmask_b32_e64 v217, 0, 32, s[4:5]
	v_ldexp_f32 v215, v215, v217
	v_log_f32_e32 v218, v215
	v_cndmask_b32_e32 v215, 0, v212, vcc
	v_sub_f32_e32 v215, v214, v215
	v_exp_f32_e32 v219, v219
	v_mul_f32_e32 v214, 0x3f317217, v218
	v_fma_f32 v214, v218, s33, -v214
	v_fmac_f32_e32 v214, 0x3377d1cf, v218
	v_fmac_f32_e32 v214, 0x3f317217, v218
	v_cmp_lt_f32_e64 vcc, |v218|, s34
	v_add_f32_e32 v223, v34, v221
	v_mul_f32_e64 v221, |v223|, s30
	v_cndmask_b32_e32 v214, v218, v214, vcc
	v_add_f32_e32 v218, 1.0, v219
	v_cmp_gt_f32_e32 vcc, s31, v218
	v_exp_f32_e32 v221, v221
	v_mul_f32_e32 v213, 0xbfb8aa3b, v213
	v_cndmask_b32_e64 v219, 0, 32, vcc
	v_ldexp_f32 v218, v218, v219
	v_log_f32_e32 v218, v218
	v_cndmask_b32_e64 v219, 0, v212, s[4:5]
	v_sub_f32_e32 v214, v214, v219
	v_exp_f32_e32 v213, v213
	v_mul_f32_e32 v219, 0x3f317217, v218
	v_fma_f32 v219, v218, s33, -v219
	v_fmac_f32_e32 v219, 0x3377d1cf, v218
	v_fmac_f32_e32 v219, 0x3f317217, v218
	v_cmp_lt_f32_e64 s[4:5], |v218|, s34
	v_mul_f32_e32 v222, 0xbfb8aa3b, v222
	v_max_f32_e32 v217, 0, v226
	v_cndmask_b32_e64 v218, v218, v219, s[4:5]
	v_add_f32_e32 v219, 1.0, v221
	v_cmp_gt_f32_e64 s[4:5], s31, v219
	v_max_f32_e32 v216, 0, v216
	v_exp_f32_e32 v222, v222
	v_cndmask_b32_e64 v221, 0, 32, s[4:5]
	v_ldexp_f32 v219, v219, v221
	v_log_f32_e32 v225, v219
	v_cndmask_b32_e32 v219, 0, v212, vcc
	v_sub_f32_e32 v219, v218, v219
	v_max_f32_e32 v221, 0, v220
	v_mul_f32_e32 v218, 0x3f317217, v225
	v_fma_f32 v218, v225, s33, -v218
	v_fmac_f32_e32 v218, 0x3377d1cf, v225
	v_fmac_f32_e32 v218, 0x3f317217, v225
	v_cmp_lt_f32_e64 vcc, |v225|, s34
	v_cndmask_b32_e64 v220, 0, v212, s[4:5]
	v_pk_add_f32 v[214:215], v[216:217], v[214:215]
	v_cndmask_b32_e32 v218, v225, v218, vcc
	v_sub_f32_e32 v218, v218, v220
	v_max_f32_e32 v220, 0, v223
	v_mul_f32_e32 v223, 0xbfb8aa3b, v224
	v_mul_f32_e32 v224, 0xbfb8aa3b, v227
	v_exp_f32_e32 v224, v224
	v_exp_f32_e32 v223, v223
	v_pk_add_f32 v[218:219], v[220:221], v[218:219]
	v_add_f32_e32 v213, 1.0, v213
	v_pk_mul_f32 v[216:217], v[214:215], s[10:11]
	v_pk_mul_f32 v[214:215], v[218:219], s[8:9] neg_lo:[0,1] neg_hi:[0,1]
	v_rcp_f32_e32 v218, v213
	v_add_f32_e32 v213, 1.0, v224
	v_rcp_f32_e32 v219, v213
	v_add_f32_e32 v213, 1.0, v223
	v_rcp_f32_e32 v220, v213
	v_add_f32_e32 v213, 1.0, v222
	s_lshl_b64 s[4:5], s[20:21], 4
	v_rcp_f32_e32 v221, v213
	s_add_u32 s20, s24, s4
	s_addc_u32 s21, s25, s5
	s_add_u32 s4, s26, s4
	s_addc_u32 s5, s27, s5
	global_store_dwordx4 v201, v[218:221], s[20:21] sc1
	global_store_dwordx4 v201, v[214:217], s[4:5] sc1

.LBB0_95:
	s_waitcnt vmcnt(7) lgkmcnt(7)
	v_pk_mul_f32 v[214:215], v[172:173], v[172:173]
	s_waitcnt lgkmcnt(6)
	v_pk_mul_f32 v[216:217], v[170:171], v[170:171]
	s_waitcnt vmcnt(4)
	v_mul_f32_e32 v213, v178, v178
	s_waitcnt lgkmcnt(5)
	v_pk_mov_b32 v[218:219], v[216:217], v[214:215] op_sel:[1,0]
	v_mov_b32_e32 v217, v215
	v_pk_add_f32 v[214:215], v[218:219], v[216:217]
	v_pk_mul_f32 v[216:217], v[168:169], v[168:169]
	v_pk_mul_f32 v[218:219], v[166:167], v[166:167]
	v_pk_add_f32 v[214:215], v[214:215], v[214:215] op_sel:[0,1] op_sel_hi:[1,0]
	s_waitcnt lgkmcnt(4)
	v_pk_mov_b32 v[220:221], v[218:219], v[216:217] op_sel:[1,0]
	v_mov_b32_e32 v219, v217
	v_pk_add_f32 v[216:217], v[220:221], v[218:219]
	v_mul_f32_e32 v218, v179, v179
	v_pk_add_f32 v[216:217], v[216:217], v[216:217] op_sel:[0,1] op_sel_hi:[1,0]
	v_mov_b32_e32 v215, v213
	v_mov_b32_e32 v217, v218
	v_pk_add_f32 v[214:215], v[214:215], v[216:217]
	v_mul_f32_e32 v216, v187, v187
	v_mul_f32_e32 v219, v180, v180
	v_pk_fma_f32 v[216:217], v[186:187], v[186:187], v[216:217] op_sel_hi:[1,1,0]
	v_mul_f32_e32 v218, v189, v189
	v_mul_f32_e32 v220, v181, v181
	v_mov_b32_e32 v217, v219
	v_pk_fma_f32 v[218:219], v[188:189], v[188:189], v[218:219] op_sel_hi:[1,1,0]
	s_ashr_i32 s17, s16, 31
	v_mov_b32_e32 v219, v220
	v_pk_add_f32 v[216:217], v[216:217], v[218:219]
	s_lshl_b64 s[4:5], s[16:17], 11
	v_pk_add_f32 v[214:215], v[214:215], v[216:217]
	s_nop 0
	v_add_f32_e32 v213, v214, v215
	s_nop 1
	v_add_f32_dpp v213, v213, v213 quad_perm:[1,0,3,2] row_mask:0xf bank_mask:0xf bound_ctrl:1
	s_nop 1
	v_add_f32_dpp v213, v213, v213 quad_perm:[2,3,0,1] row_mask:0xf bank_mask:0xf bound_ctrl:1
	s_nop 1
	v_add_f32_dpp v213, v213, v213 row_half_mirror row_mask:0xf bank_mask:0xf bound_ctrl:1
	s_nop 1
	v_add_f32_dpp v213, v213, v213 row_mirror row_mask:0xf bank_mask:0xf bound_ctrl:1
	ds_bpermute_b32 v214, v200, v213
	s_waitcnt lgkmcnt(0)
	v_add_f32_e32 v213, v213, v214
	ds_bpermute_b32 v214, v203, v213
	s_waitcnt lgkmcnt(0)
	v_add_f32_e32 v213, v213, v214
	v_fmamk_f32 v213, v213, 0x3a800000, v211
	v_rsq_f32_e32 v230, v213
	ds_read_b128 v[214:217], v210
	ds_read_b128 v[218:221], v210 offset:4096
	ds_read_b128 v[222:225], v210 offset:1024
	ds_read_b128 v[226:229], v210 offset:5120
	v_pk_mul_f32 v[170:171], v[170:171], v[230:231] op_sel_hi:[1,0]
	v_pk_mul_f32 v[172:173], v[172:173], v[230:231] op_sel_hi:[1,0]
	s_waitcnt lgkmcnt(2)
	v_pk_fma_f32 v[170:171], v[214:215], v[170:171], v[218:219]
	v_pk_fma_f32 v[172:173], v[216:217], v[172:173], v[220:221]
	ds_read_b128 v[214:217], v210 offset:2048
	ds_read_b128 v[218:221], v210 offset:6144
	v_pk_mul_f32 v[166:167], v[166:167], v[230:231] op_sel_hi:[1,0]
	v_pk_mul_f32 v[168:169], v[168:169], v[230:231] op_sel_hi:[1,0]
	s_waitcnt lgkmcnt(2)
	v_pk_fma_f32 v[166:167], v[222:223], v[166:167], v[226:227]
	v_pk_fma_f32 v[168:169], v[224:225], v[168:169], v[228:229]
	ds_read_b128 v[222:225], v210 offset:3072
	ds_read_b128 v[226:229], v210 offset:7168
	v_pk_mul_f32 v[186:187], v[186:187], v[230:231] op_sel_hi:[1,0]
	v_pk_mul_f32 v[188:189], v[188:189], v[230:231] op_sel_hi:[1,0]
	s_waitcnt lgkmcnt(2)
	v_pk_fma_f32 v[186:187], v[214:215], v[186:187], v[218:219]
	v_pk_fma_f32 v[188:189], v[216:217], v[188:189], v[220:221]
	v_lshl_add_u64 v[214:215], v[206:207], 0, s[4:5]
	v_cvt_pk_bf16_f32 v216, v170, v171
	v_cvt_pk_bf16_f32 v217, v172, v173
	v_pk_mul_f32 v[178:179], v[178:179], v[230:231] op_sel_hi:[1,0]
	v_pk_mul_f32 v[180:181], v[180:181], v[230:231] op_sel_hi:[1,0]
	global_store_dwordx2 v[214:215], v[216:217], off
	v_cvt_pk_bf16_f32 v216, v166, v167
	v_cvt_pk_bf16_f32 v217, v168, v169
	s_waitcnt lgkmcnt(0)
	v_pk_fma_f32 v[180:181], v[224:225], v[180:181], v[228:229]
	v_pk_fma_f32 v[178:179], v[222:223], v[178:179], v[226:227]
	global_store_dwordx2 v[214:215], v[216:217], off offset:512
	v_cvt_pk_bf16_f32 v216, v186, v187
	v_cvt_pk_bf16_f32 v217, v188, v189
	global_store_dwordx2 v[214:215], v[216:217], off offset:1024
	v_cvt_pk_bf16_f32 v216, v178, v179
	v_cvt_pk_bf16_f32 v217, v180, v181
	global_store_dwordx2 v[214:215], v[216:217], off offset:1536
	v_fma_f32 v213, v170, v162, 0
	v_fma_f32 v214, v171, v163, 0
	v_fmac_f32_e32 v213, v172, v164
	v_fmac_f32_e32 v214, v173, v165
	v_fmac_f32_e32 v213, v166, v158
	v_fmac_f32_e32 v214, v167, v159
	v_fmac_f32_e32 v213, v168, v160
	v_fmac_f32_e32 v214, v169, v161
	v_fmac_f32_e32 v213, v186, v154
	v_fmac_f32_e32 v214, v187, v155
	v_fmac_f32_e32 v213, v188, v156
	v_fmac_f32_e32 v214, v189, v157
	v_fmac_f32_e32 v213, v178, v150
	v_fmac_f32_e32 v214, v179, v151
	v_fmac_f32_e32 v213, v180, v152
	v_fmac_f32_e32 v214, v181, v153
	v_add_f32_e32 v213, v213, v214
	v_fma_f32 v214, v170, v146, 0
	v_fma_f32 v215, v171, v147, 0
	v_fmac_f32_e32 v214, v172, v148
	v_fmac_f32_e32 v215, v173, v149
	v_fmac_f32_e32 v214, v166, v142
	v_fmac_f32_e32 v215, v167, v143
	v_fmac_f32_e32 v214, v168, v144
	v_fmac_f32_e32 v215, v169, v145
	v_fmac_f32_e32 v214, v186, v138
	v_fmac_f32_e32 v215, v187, v139
	v_fmac_f32_e32 v214, v188, v140
	v_fmac_f32_e32 v215, v189, v141
	v_fmac_f32_e32 v214, v178, v134
	v_fmac_f32_e32 v215, v179, v135
	v_fmac_f32_e32 v214, v180, v136
	v_fmac_f32_e32 v215, v181, v137
	v_add_f32_e32 v214, v214, v215
	v_fma_f32 v216, v171, v131, 0
	v_fmac_f32_e32 v216, v173, v133
	v_add_f32_dpp v214, v214, v214 quad_perm:[1,0,3,2] row_mask:0xf bank_mask:0xf bound_ctrl:1
	v_fmac_f32_e32 v216, v167, v127
	v_fmac_f32_e32 v216, v169, v129
	v_add_f32_dpp v214, v214, v214 quad_perm:[2,3,0,1] row_mask:0xf bank_mask:0xf bound_ctrl:1
	v_fmac_f32_e32 v216, v187, v123
	v_fmac_f32_e32 v216, v189, v125
	v_add_f32_dpp v214, v214, v214 row_half_mirror row_mask:0xf bank_mask:0xf bound_ctrl:1
	v_fmac_f32_e32 v216, v179, v119
	v_fmac_f32_e32 v216, v181, v121
	v_add_f32_dpp v215, v214, v214 row_mirror row_mask:0xf bank_mask:0xf bound_ctrl:1
	v_fma_f32 v214, v170, v130, 0
	v_fmac_f32_e32 v214, v172, v132
	v_fmac_f32_e32 v214, v166, v126
	v_fmac_f32_e32 v214, v168, v128
	v_fmac_f32_e32 v214, v186, v122
	v_fmac_f32_e32 v214, v188, v124
	v_fmac_f32_e32 v214, v178, v118
	v_fmac_f32_e32 v214, v180, v120
	v_add_f32_e32 v214, v214, v216
	v_fma_f32 v216, v171, v115, 0
	v_fmac_f32_e32 v216, v173, v117
	v_add_f32_dpp v214, v214, v214 quad_perm:[1,0,3,2] row_mask:0xf bank_mask:0xf bound_ctrl:1
	v_fmac_f32_e32 v216, v167, v111
	v_fmac_f32_e32 v216, v169, v113
	v_add_f32_dpp v214, v214, v214 quad_perm:[2,3,0,1] row_mask:0xf bank_mask:0xf bound_ctrl:1
	v_fmac_f32_e32 v216, v187, v107
	v_fmac_f32_e32 v216, v189, v109
	v_add_f32_dpp v214, v214, v214 row_half_mirror row_mask:0xf bank_mask:0xf bound_ctrl:1
	v_fmac_f32_e32 v216, v179, v103
	v_fmac_f32_e32 v216, v181, v105
	v_add_f32_dpp v217, v214, v214 row_mirror row_mask:0xf bank_mask:0xf bound_ctrl:1
	v_fma_f32 v214, v170, v114, 0
	v_fmac_f32_e32 v214, v172, v116
	v_fmac_f32_e32 v214, v166, v110
	v_fmac_f32_e32 v214, v168, v112
	v_fmac_f32_e32 v214, v186, v106
	v_fmac_f32_e32 v214, v188, v108
	v_fmac_f32_e32 v214, v178, v102
	v_fmac_f32_e32 v214, v180, v104
	v_add_f32_e32 v214, v214, v216
	v_fma_f32 v216, v171, v99, 0
	v_fmac_f32_e32 v216, v173, v101
	v_add_f32_dpp v214, v214, v214 quad_perm:[1,0,3,2] row_mask:0xf bank_mask:0xf bound_ctrl:1
	v_fmac_f32_e32 v216, v167, v95
	v_fmac_f32_e32 v216, v169, v97
	v_add_f32_dpp v214, v214, v214 quad_perm:[2,3,0,1] row_mask:0xf bank_mask:0xf bound_ctrl:1
	v_fmac_f32_e32 v216, v187, v91
	v_fmac_f32_e32 v216, v189, v93
	v_add_f32_dpp v214, v214, v214 row_half_mirror row_mask:0xf bank_mask:0xf bound_ctrl:1
	v_fmac_f32_e32 v216, v179, v87
	v_fmac_f32_e32 v216, v181, v89
	v_add_f32_dpp v219, v214, v214 row_mirror row_mask:0xf bank_mask:0xf bound_ctrl:1
	v_fma_f32 v214, v170, v98, 0
	v_fmac_f32_e32 v214, v172, v100
	v_fmac_f32_e32 v214, v166, v94
	v_fmac_f32_e32 v214, v168, v96
	v_fmac_f32_e32 v214, v186, v90
	v_fmac_f32_e32 v214, v188, v92
	v_fmac_f32_e32 v214, v178, v86
	v_fmac_f32_e32 v214, v180, v88
	v_add_f32_e32 v214, v214, v216
	v_fma_f32 v216, v171, v83, 0
	v_fmac_f32_e32 v216, v173, v85
	v_add_f32_dpp v214, v214, v214 quad_perm:[1,0,3,2] row_mask:0xf bank_mask:0xf bound_ctrl:1
	v_fmac_f32_e32 v216, v167, v79
	v_fmac_f32_e32 v216, v169, v81
	v_add_f32_dpp v214, v214, v214 quad_perm:[2,3,0,1] row_mask:0xf bank_mask:0xf bound_ctrl:1
	v_fmac_f32_e32 v216, v187, v75
	v_fmac_f32_e32 v216, v189, v77
	v_add_f32_dpp v214, v214, v214 row_half_mirror row_mask:0xf bank_mask:0xf bound_ctrl:1
	v_fmac_f32_e32 v216, v179, v71
	v_fmac_f32_e32 v216, v181, v73
	v_add_f32_dpp v221, v214, v214 row_mirror row_mask:0xf bank_mask:0xf bound_ctrl:1
	v_fma_f32 v214, v170, v82, 0
	v_fmac_f32_e32 v214, v172, v84
	v_fmac_f32_e32 v214, v166, v78
	v_fmac_f32_e32 v214, v168, v80
	v_fmac_f32_e32 v214, v186, v74
	v_fmac_f32_e32 v214, v188, v76
	v_fmac_f32_e32 v214, v178, v70
	v_fmac_f32_e32 v214, v180, v72
	v_add_f32_e32 v214, v214, v216
	v_fma_f32 v216, v171, v67, 0
	v_fmac_f32_e32 v216, v173, v69
	v_add_f32_dpp v214, v214, v214 quad_perm:[1,0,3,2] row_mask:0xf bank_mask:0xf bound_ctrl:1
	v_fmac_f32_e32 v216, v167, v63
	v_fmac_f32_e32 v216, v169, v65
	v_add_f32_dpp v214, v214, v214 quad_perm:[2,3,0,1] row_mask:0xf bank_mask:0xf bound_ctrl:1
	v_fmac_f32_e32 v216, v187, v59
	v_fmac_f32_e32 v216, v189, v61
	v_add_f32_dpp v214, v214, v214 row_half_mirror row_mask:0xf bank_mask:0xf bound_ctrl:1
	v_fmac_f32_e32 v216, v179, v55
	v_fmac_f32_e32 v216, v181, v57
	v_add_f32_dpp v223, v214, v214 row_mirror row_mask:0xf bank_mask:0xf bound_ctrl:1
	v_fma_f32 v214, v170, v66, 0
	v_fmac_f32_e32 v214, v172, v68
	v_fmac_f32_e32 v214, v166, v62
	v_fmac_f32_e32 v214, v168, v64
	v_fmac_f32_e32 v214, v186, v58
	v_fmac_f32_e32 v214, v188, v60
	v_fmac_f32_e32 v214, v178, v54
	v_fmac_f32_e32 v214, v180, v56
	v_add_f32_e32 v214, v214, v216
	v_fma_f32 v216, v171, v51, 0
	v_fmac_f32_e32 v216, v173, v53
	v_add_f32_dpp v214, v214, v214 quad_perm:[1,0,3,2] row_mask:0xf bank_mask:0xf bound_ctrl:1
	v_fmac_f32_e32 v216, v167, v47
	v_fmac_f32_e32 v216, v169, v49
	v_add_f32_dpp v214, v214, v214 quad_perm:[2,3,0,1] row_mask:0xf bank_mask:0xf bound_ctrl:1
	v_fmac_f32_e32 v216, v187, v43
	v_fmac_f32_e32 v216, v189, v45
	v_add_f32_dpp v214, v214, v214 row_half_mirror row_mask:0xf bank_mask:0xf bound_ctrl:1
	v_fmac_f32_e32 v216, v179, v39
	v_fmac_f32_e32 v216, v181, v41
	v_add_f32_dpp v225, v214, v214 row_mirror row_mask:0xf bank_mask:0xf bound_ctrl:1
	v_fma_f32 v214, v170, v50, 0
	v_fmac_f32_e32 v214, v172, v52
	v_fmac_f32_e32 v214, v166, v46
	v_fmac_f32_e32 v214, v168, v48
	v_fmac_f32_e32 v214, v186, v42
	v_fmac_f32_e32 v214, v188, v44
	v_fmac_f32_e32 v214, v178, v38
	v_fmac_f32_e32 v214, v180, v40
	v_add_f32_e32 v214, v214, v216
	v_add_f32_dpp v213, v213, v213 quad_perm:[1,0,3,2] row_mask:0xf bank_mask:0xf bound_ctrl:1
	ds_bpermute_b32 v218, v200, v215
	v_add_f32_dpp v214, v214, v214 quad_perm:[1,0,3,2] row_mask:0xf bank_mask:0xf bound_ctrl:1
	v_add_f32_dpp v213, v213, v213 quad_perm:[2,3,0,1] row_mask:0xf bank_mask:0xf bound_ctrl:1
	ds_bpermute_b32 v220, v200, v217
	v_add_f32_dpp v214, v214, v214 quad_perm:[2,3,0,1] row_mask:0xf bank_mask:0xf bound_ctrl:1
	v_add_f32_dpp v213, v213, v213 row_half_mirror row_mask:0xf bank_mask:0xf bound_ctrl:1
	ds_bpermute_b32 v222, v200, v219
	v_add_f32_dpp v214, v214, v214 row_half_mirror row_mask:0xf bank_mask:0xf bound_ctrl:1
	v_add_f32_dpp v213, v213, v213 row_mirror row_mask:0xf bank_mask:0xf bound_ctrl:1
	ds_bpermute_b32 v216, v200, v213
	v_add_f32_dpp v227, v214, v214 row_mirror row_mask:0xf bank_mask:0xf bound_ctrl:1
	ds_bpermute_b32 v224, v200, v221
	ds_bpermute_b32 v226, v200, v223
	ds_bpermute_b32 v228, v200, v225
	ds_bpermute_b32 v229, v200, v227
	s_waitcnt lgkmcnt(4)
	v_add_f32_e32 v213, v213, v216
	v_add_f32_e32 v215, v215, v218
	v_add_f32_e32 v217, v217, v220
	v_add_f32_e32 v219, v219, v222
	s_waitcnt lgkmcnt(3)
	v_add_f32_e32 v221, v221, v224
	s_waitcnt lgkmcnt(2)
	v_add_f32_e32 v223, v223, v226
	s_waitcnt lgkmcnt(1)
	v_add_f32_e32 v225, v225, v228
	s_waitcnt lgkmcnt(0)
	v_add_f32_e32 v227, v227, v229
	ds_bpermute_b32 v214, v203, v213
	ds_bpermute_b32 v216, v203, v215
	ds_bpermute_b32 v218, v203, v217
	ds_bpermute_b32 v220, v203, v219
	ds_bpermute_b32 v222, v203, v221
	ds_bpermute_b32 v224, v203, v223
	ds_bpermute_b32 v226, v203, v225
	ds_bpermute_b32 v228, v203, v227
	s_and_saveexec_b64 s[18:19], s[2:3]
	s_cbranch_execz .LBB0_97
	s_waitcnt lgkmcnt(0)
	v_add_f32_e32 v227, v227, v228
	v_add_f32_e32 v225, v225, v226
	v_add_f32_e32 v226, v37, v227
	v_mul_f32_e64 v227, |v226|, s30
	v_exp_f32_e32 v227, v227
	v_add_f32_e32 v221, v221, v222
	v_add_f32_e32 v222, v219, v220
	v_add_f32_e32 v213, v213, v214
	v_add_f32_e32 v219, 1.0, v227
	v_cmp_gt_f32_e32 vcc, s31, v219
	v_add_f32_e32 v227, v215, v216
	v_add_f32_e32 v216, v36, v225
	v_cndmask_b32_e64 v220, 0, 32, vcc
	v_ldexp_f32 v219, v219, v220
	v_log_f32_e32 v219, v219
	v_mul_f32_e64 v215, |v216|, s30
	v_exp_f32_e32 v215, v215
	v_add_f32_e32 v223, v223, v224
	v_mul_f32_e32 v214, 0x3f317217, v219
	v_fma_f32 v214, v219, s33, -v214
	v_fmac_f32_e32 v214, 0x3377d1cf, v219
	v_fmac_f32_e32 v214, 0x3f317217, v219
	v_cmp_lt_f32_e64 s[4:5], |v219|, s34
	v_add_f32_e32 v215, 1.0, v215
	v_add_f32_e32 v224, v217, v218
	v_cndmask_b32_e64 v214, v219, v214, s[4:5]
	v_cmp_gt_f32_e64 s[4:5], s31, v215
	v_add_f32_e32 v220, v35, v223
	v_mul_f32_e64 v219, |v220|, s30
	v_cndmask_b32_e64 v217, 0, 32, s[4:5]
	v_ldexp_f32 v215, v215, v217
	v_log_f32_e32 v218, v215
	v_cndmask_b32_e32 v215, 0, v212, vcc
	v_sub_f32_e32 v215, v214, v215
	v_exp_f32_e32 v219, v219
	v_mul_f32_e32 v214, 0x3f317217, v218
	v_fma_f32 v214, v218, s33, -v214
	v_fmac_f32_e32 v214, 0x3377d1cf, v218
	v_fmac_f32_e32 v214, 0x3f317217, v218
	v_cmp_lt_f32_e64 vcc, |v218|, s34
	v_add_f32_e32 v223, v34, v221
	v_mul_f32_e64 v221, |v223|, s30
	v_cndmask_b32_e32 v214, v218, v214, vcc
	v_add_f32_e32 v218, 1.0, v219
	v_cmp_gt_f32_e32 vcc, s31, v218
	v_exp_f32_e32 v221, v221
	v_mul_f32_e32 v213, 0xbfb8aa3b, v213
	v_cndmask_b32_e64 v219, 0, 32, vcc
	v_ldexp_f32 v218, v218, v219
	v_log_f32_e32 v218, v218
	v_cndmask_b32_e64 v219, 0, v212, s[4:5]
	v_sub_f32_e32 v214, v214, v219
	v_exp_f32_e32 v213, v213
	v_mul_f32_e32 v219, 0x3f317217, v218
	v_fma_f32 v219, v218, s33, -v219
	v_fmac_f32_e32 v219, 0x3377d1cf, v218
	v_fmac_f32_e32 v219, 0x3f317217, v218
	v_cmp_lt_f32_e64 s[4:5], |v218|, s34
	v_mul_f32_e32 v222, 0xbfb8aa3b, v222
	v_max_f32_e32 v217, 0, v226
	v_cndmask_b32_e64 v218, v218, v219, s[4:5]
	v_add_f32_e32 v219, 1.0, v221
	v_cmp_gt_f32_e64 s[4:5], s31, v219
	v_max_f32_e32 v216, 0, v216
	v_exp_f32_e32 v222, v222
	v_cndmask_b32_e64 v221, 0, 32, s[4:5]
	v_ldexp_f32 v219, v219, v221
	v_log_f32_e32 v225, v219
	v_cndmask_b32_e32 v219, 0, v212, vcc
	v_sub_f32_e32 v219, v218, v219
	v_max_f32_e32 v221, 0, v220
	v_mul_f32_e32 v218, 0x3f317217, v225
	v_fma_f32 v218, v225, s33, -v218
	v_fmac_f32_e32 v218, 0x3377d1cf, v225
	v_fmac_f32_e32 v218, 0x3f317217, v225
	v_cmp_lt_f32_e64 vcc, |v225|, s34
	v_cndmask_b32_e64 v220, 0, v212, s[4:5]
	v_pk_add_f32 v[214:215], v[216:217], v[214:215]
	v_cndmask_b32_e32 v218, v225, v218, vcc
	v_sub_f32_e32 v218, v218, v220
	v_max_f32_e32 v220, 0, v223
	v_mul_f32_e32 v223, 0xbfb8aa3b, v224
	v_mul_f32_e32 v224, 0xbfb8aa3b, v227
	v_exp_f32_e32 v224, v224
	v_exp_f32_e32 v223, v223
	v_pk_add_f32 v[218:219], v[220:221], v[218:219]
	v_add_f32_e32 v213, 1.0, v213
	v_pk_mul_f32 v[216:217], v[214:215], s[10:11]
	v_pk_mul_f32 v[214:215], v[218:219], s[8:9] neg_lo:[0,1] neg_hi:[0,1]
	v_rcp_f32_e32 v218, v213
	v_add_f32_e32 v213, 1.0, v224
	v_rcp_f32_e32 v219, v213
	v_add_f32_e32 v213, 1.0, v223
	v_rcp_f32_e32 v220, v213
	v_add_f32_e32 v213, 1.0, v222
	s_lshl_b64 s[4:5], s[16:17], 4
	v_rcp_f32_e32 v221, v213
	s_add_u32 s16, s24, s4
	s_addc_u32 s17, s25, s5
	s_add_u32 s4, s26, s4
	s_addc_u32 s5, s27, s5
	global_store_dwordx4 v201, v[218:221], s[16:17] sc1
	global_store_dwordx4 v201, v[214:217], s[4:5] sc1

.LBB0_98:
	s_waitcnt vmcnt(7) lgkmcnt(7)
	v_pk_mul_f32 v[214:215], v[184:185], v[184:185]
	s_waitcnt lgkmcnt(6)
	v_pk_mul_f32 v[216:217], v[182:183], v[182:183]
	s_waitcnt vmcnt(4)
	v_mul_f32_e32 v213, v190, v190
	s_waitcnt lgkmcnt(5)
	v_pk_mov_b32 v[218:219], v[216:217], v[214:215] op_sel:[1,0]
	v_mov_b32_e32 v217, v215
	v_pk_add_f32 v[214:215], v[218:219], v[216:217]
	v_pk_mul_f32 v[216:217], v[176:177], v[176:177]
	v_pk_mul_f32 v[218:219], v[174:175], v[174:175]
	v_pk_add_f32 v[214:215], v[214:215], v[214:215] op_sel:[0,1] op_sel_hi:[1,0]
	s_waitcnt lgkmcnt(4)
	v_pk_mov_b32 v[220:221], v[218:219], v[216:217] op_sel:[1,0]
	v_mov_b32_e32 v219, v217
	v_pk_add_f32 v[216:217], v[220:221], v[218:219]
	v_mul_f32_e32 v218, v191, v191
	v_pk_add_f32 v[216:217], v[216:217], v[216:217] op_sel:[0,1] op_sel_hi:[1,0]
	v_mov_b32_e32 v215, v213
	v_mov_b32_e32 v217, v218
	v_pk_add_f32 v[214:215], v[214:215], v[216:217]
	v_mul_f32_e32 v216, v195, v195
	v_mul_f32_e32 v219, v192, v192
	v_pk_fma_f32 v[216:217], v[194:195], v[194:195], v[216:217] op_sel_hi:[1,1,0]
	v_mul_f32_e32 v218, v197, v197
	v_mul_f32_e32 v220, v193, v193
	v_mov_b32_e32 v217, v219
	v_pk_fma_f32 v[218:219], v[196:197], v[196:197], v[218:219] op_sel_hi:[1,1,0]
	s_ashr_i32 s13, s12, 31
	v_mov_b32_e32 v219, v220
	v_pk_add_f32 v[216:217], v[216:217], v[218:219]
	s_lshl_b64 s[4:5], s[12:13], 11
	v_pk_add_f32 v[214:215], v[214:215], v[216:217]
	s_nop 0
	v_add_f32_e32 v213, v214, v215
	s_nop 1
	v_add_f32_dpp v213, v213, v213 quad_perm:[1,0,3,2] row_mask:0xf bank_mask:0xf bound_ctrl:1
	s_nop 1
	v_add_f32_dpp v213, v213, v213 quad_perm:[2,3,0,1] row_mask:0xf bank_mask:0xf bound_ctrl:1
	s_nop 1
	v_add_f32_dpp v213, v213, v213 row_half_mirror row_mask:0xf bank_mask:0xf bound_ctrl:1
	s_nop 1
	v_add_f32_dpp v213, v213, v213 row_mirror row_mask:0xf bank_mask:0xf bound_ctrl:1
	ds_bpermute_b32 v214, v200, v213
	s_waitcnt lgkmcnt(0)
	v_add_f32_e32 v213, v213, v214
	ds_bpermute_b32 v214, v203, v213
	s_waitcnt lgkmcnt(0)
	v_add_f32_e32 v213, v213, v214
	v_fmamk_f32 v213, v213, 0x3a800000, v211
	v_rsq_f32_e32 v230, v213
	ds_read_b128 v[214:217], v210
	ds_read_b128 v[218:221], v210 offset:4096
	ds_read_b128 v[222:225], v210 offset:1024
	ds_read_b128 v[226:229], v210 offset:5120
	v_pk_mul_f32 v[182:183], v[182:183], v[230:231] op_sel_hi:[1,0]
	v_pk_mul_f32 v[184:185], v[184:185], v[230:231] op_sel_hi:[1,0]
	s_waitcnt lgkmcnt(2)
	v_pk_fma_f32 v[182:183], v[214:215], v[182:183], v[218:219]
	v_pk_fma_f32 v[184:185], v[216:217], v[184:185], v[220:221]
	ds_read_b128 v[214:217], v210 offset:2048
	ds_read_b128 v[218:221], v210 offset:6144
	v_pk_mul_f32 v[174:175], v[174:175], v[230:231] op_sel_hi:[1,0]
	v_pk_mul_f32 v[176:177], v[176:177], v[230:231] op_sel_hi:[1,0]
	s_waitcnt lgkmcnt(2)
	v_pk_fma_f32 v[174:175], v[222:223], v[174:175], v[226:227]
	v_pk_fma_f32 v[176:177], v[224:225], v[176:177], v[228:229]
	ds_read_b128 v[222:225], v210 offset:3072
	ds_read_b128 v[226:229], v210 offset:7168
	v_pk_mul_f32 v[194:195], v[194:195], v[230:231] op_sel_hi:[1,0]
	v_pk_mul_f32 v[196:197], v[196:197], v[230:231] op_sel_hi:[1,0]
	s_waitcnt lgkmcnt(2)
	v_pk_fma_f32 v[194:195], v[214:215], v[194:195], v[218:219]
	v_pk_fma_f32 v[196:197], v[216:217], v[196:197], v[220:221]
	v_lshl_add_u64 v[214:215], v[206:207], 0, s[4:5]
	v_cvt_pk_bf16_f32 v216, v182, v183
	v_cvt_pk_bf16_f32 v217, v184, v185
	v_pk_mul_f32 v[190:191], v[190:191], v[230:231] op_sel_hi:[1,0]
	v_pk_mul_f32 v[192:193], v[192:193], v[230:231] op_sel_hi:[1,0]
	global_store_dwordx2 v[214:215], v[216:217], off
	v_cvt_pk_bf16_f32 v216, v174, v175
	v_cvt_pk_bf16_f32 v217, v176, v177
	s_waitcnt lgkmcnt(0)
	v_pk_fma_f32 v[192:193], v[224:225], v[192:193], v[228:229]
	v_pk_fma_f32 v[190:191], v[222:223], v[190:191], v[226:227]
	global_store_dwordx2 v[214:215], v[216:217], off offset:512
	v_cvt_pk_bf16_f32 v216, v194, v195
	v_cvt_pk_bf16_f32 v217, v196, v197
	global_store_dwordx2 v[214:215], v[216:217], off offset:1024
	v_cvt_pk_bf16_f32 v216, v190, v191
	v_cvt_pk_bf16_f32 v217, v192, v193
	global_store_dwordx2 v[214:215], v[216:217], off offset:1536
	v_fma_f32 v213, v182, v162, 0
	v_fma_f32 v214, v183, v163, 0
	v_fmac_f32_e32 v213, v184, v164
	v_fmac_f32_e32 v214, v185, v165
	v_fmac_f32_e32 v213, v174, v158
	v_fmac_f32_e32 v214, v175, v159
	v_fmac_f32_e32 v213, v176, v160
	v_fmac_f32_e32 v214, v177, v161
	v_fmac_f32_e32 v213, v194, v154
	v_fmac_f32_e32 v214, v195, v155
	v_fmac_f32_e32 v213, v196, v156
	v_fmac_f32_e32 v214, v197, v157
	v_fmac_f32_e32 v213, v190, v150
	v_fmac_f32_e32 v214, v191, v151
	v_fmac_f32_e32 v213, v192, v152
	v_fmac_f32_e32 v214, v193, v153
	v_add_f32_e32 v213, v213, v214
	v_fma_f32 v214, v182, v146, 0
	v_fma_f32 v215, v183, v147, 0
	v_fmac_f32_e32 v214, v184, v148
	v_fmac_f32_e32 v215, v185, v149
	v_fmac_f32_e32 v214, v174, v142
	v_fmac_f32_e32 v215, v175, v143
	v_fmac_f32_e32 v214, v176, v144
	v_fmac_f32_e32 v215, v177, v145
	v_fmac_f32_e32 v214, v194, v138
	v_fmac_f32_e32 v215, v195, v139
	v_fmac_f32_e32 v214, v196, v140
	v_fmac_f32_e32 v215, v197, v141
	v_fmac_f32_e32 v214, v190, v134
	v_fmac_f32_e32 v215, v191, v135
	v_fmac_f32_e32 v214, v192, v136
	v_fmac_f32_e32 v215, v193, v137
	v_add_f32_e32 v214, v214, v215
	v_fma_f32 v216, v183, v131, 0
	v_fmac_f32_e32 v216, v185, v133
	v_add_f32_dpp v214, v214, v214 quad_perm:[1,0,3,2] row_mask:0xf bank_mask:0xf bound_ctrl:1
	v_fmac_f32_e32 v216, v175, v127
	v_fmac_f32_e32 v216, v177, v129
	v_add_f32_dpp v214, v214, v214 quad_perm:[2,3,0,1] row_mask:0xf bank_mask:0xf bound_ctrl:1
	v_fmac_f32_e32 v216, v195, v123
	v_fmac_f32_e32 v216, v197, v125
	v_add_f32_dpp v214, v214, v214 row_half_mirror row_mask:0xf bank_mask:0xf bound_ctrl:1
	v_fmac_f32_e32 v216, v191, v119
	v_fmac_f32_e32 v216, v193, v121
	v_add_f32_dpp v215, v214, v214 row_mirror row_mask:0xf bank_mask:0xf bound_ctrl:1
	v_fma_f32 v214, v182, v130, 0
	v_fmac_f32_e32 v214, v184, v132
	v_fmac_f32_e32 v214, v174, v126
	v_fmac_f32_e32 v214, v176, v128
	v_fmac_f32_e32 v214, v194, v122
	v_fmac_f32_e32 v214, v196, v124
	v_fmac_f32_e32 v214, v190, v118
	v_fmac_f32_e32 v214, v192, v120
	v_add_f32_e32 v214, v214, v216
	v_fma_f32 v216, v183, v115, 0
	v_fmac_f32_e32 v216, v185, v117
	v_add_f32_dpp v214, v214, v214 quad_perm:[1,0,3,2] row_mask:0xf bank_mask:0xf bound_ctrl:1
	v_fmac_f32_e32 v216, v175, v111
	v_fmac_f32_e32 v216, v177, v113
	v_add_f32_dpp v214, v214, v214 quad_perm:[2,3,0,1] row_mask:0xf bank_mask:0xf bound_ctrl:1
	v_fmac_f32_e32 v216, v195, v107
	v_fmac_f32_e32 v216, v197, v109
	v_add_f32_dpp v214, v214, v214 row_half_mirror row_mask:0xf bank_mask:0xf bound_ctrl:1
	v_fmac_f32_e32 v216, v191, v103
	v_fmac_f32_e32 v216, v193, v105
	v_add_f32_dpp v217, v214, v214 row_mirror row_mask:0xf bank_mask:0xf bound_ctrl:1
	v_fma_f32 v214, v182, v114, 0
	v_fmac_f32_e32 v214, v184, v116
	v_fmac_f32_e32 v214, v174, v110
	v_fmac_f32_e32 v214, v176, v112
	v_fmac_f32_e32 v214, v194, v106
	v_fmac_f32_e32 v214, v196, v108
	v_fmac_f32_e32 v214, v190, v102
	v_fmac_f32_e32 v214, v192, v104
	v_add_f32_e32 v214, v214, v216
	v_fma_f32 v216, v183, v99, 0
	v_fmac_f32_e32 v216, v185, v101
	v_add_f32_dpp v214, v214, v214 quad_perm:[1,0,3,2] row_mask:0xf bank_mask:0xf bound_ctrl:1
	v_fmac_f32_e32 v216, v175, v95
	v_fmac_f32_e32 v216, v177, v97
	v_add_f32_dpp v214, v214, v214 quad_perm:[2,3,0,1] row_mask:0xf bank_mask:0xf bound_ctrl:1
	v_fmac_f32_e32 v216, v195, v91
	v_fmac_f32_e32 v216, v197, v93
	v_add_f32_dpp v214, v214, v214 row_half_mirror row_mask:0xf bank_mask:0xf bound_ctrl:1
	v_fmac_f32_e32 v216, v191, v87
	v_fmac_f32_e32 v216, v193, v89
	v_add_f32_dpp v219, v214, v214 row_mirror row_mask:0xf bank_mask:0xf bound_ctrl:1
	v_fma_f32 v214, v182, v98, 0
	v_fmac_f32_e32 v214, v184, v100
	v_fmac_f32_e32 v214, v174, v94
	v_fmac_f32_e32 v214, v176, v96
	v_fmac_f32_e32 v214, v194, v90
	v_fmac_f32_e32 v214, v196, v92
	v_fmac_f32_e32 v214, v190, v86
	v_fmac_f32_e32 v214, v192, v88
	v_add_f32_e32 v214, v214, v216
	v_fma_f32 v216, v183, v83, 0
	v_fmac_f32_e32 v216, v185, v85
	v_add_f32_dpp v214, v214, v214 quad_perm:[1,0,3,2] row_mask:0xf bank_mask:0xf bound_ctrl:1
	v_fmac_f32_e32 v216, v175, v79
	v_fmac_f32_e32 v216, v177, v81
	v_add_f32_dpp v214, v214, v214 quad_perm:[2,3,0,1] row_mask:0xf bank_mask:0xf bound_ctrl:1
	v_fmac_f32_e32 v216, v195, v75
	v_fmac_f32_e32 v216, v197, v77
	v_add_f32_dpp v214, v214, v214 row_half_mirror row_mask:0xf bank_mask:0xf bound_ctrl:1
	v_fmac_f32_e32 v216, v191, v71
	v_fmac_f32_e32 v216, v193, v73
	v_add_f32_dpp v221, v214, v214 row_mirror row_mask:0xf bank_mask:0xf bound_ctrl:1
	v_fma_f32 v214, v182, v82, 0
	v_fmac_f32_e32 v214, v184, v84
	v_fmac_f32_e32 v214, v174, v78
	v_fmac_f32_e32 v214, v176, v80
	v_fmac_f32_e32 v214, v194, v74
	v_fmac_f32_e32 v214, v196, v76
	v_fmac_f32_e32 v214, v190, v70
	v_fmac_f32_e32 v214, v192, v72
	v_add_f32_e32 v214, v214, v216
	v_fma_f32 v216, v183, v67, 0
	v_fmac_f32_e32 v216, v185, v69
	v_add_f32_dpp v214, v214, v214 quad_perm:[1,0,3,2] row_mask:0xf bank_mask:0xf bound_ctrl:1
	v_fmac_f32_e32 v216, v175, v63
	v_fmac_f32_e32 v216, v177, v65
	v_add_f32_dpp v214, v214, v214 quad_perm:[2,3,0,1] row_mask:0xf bank_mask:0xf bound_ctrl:1
	v_fmac_f32_e32 v216, v195, v59
	v_fmac_f32_e32 v216, v197, v61
	v_add_f32_dpp v214, v214, v214 row_half_mirror row_mask:0xf bank_mask:0xf bound_ctrl:1
	v_fmac_f32_e32 v216, v191, v55
	v_fmac_f32_e32 v216, v193, v57
	v_add_f32_dpp v223, v214, v214 row_mirror row_mask:0xf bank_mask:0xf bound_ctrl:1
	v_fma_f32 v214, v182, v66, 0
	v_fmac_f32_e32 v214, v184, v68
	v_fmac_f32_e32 v214, v174, v62
	v_fmac_f32_e32 v214, v176, v64
	v_fmac_f32_e32 v214, v194, v58
	v_fmac_f32_e32 v214, v196, v60
	v_fmac_f32_e32 v214, v190, v54
	v_fmac_f32_e32 v214, v192, v56
	v_add_f32_e32 v214, v214, v216
	v_fma_f32 v216, v183, v51, 0
	v_fmac_f32_e32 v216, v185, v53
	v_add_f32_dpp v214, v214, v214 quad_perm:[1,0,3,2] row_mask:0xf bank_mask:0xf bound_ctrl:1
	v_fmac_f32_e32 v216, v175, v47
	v_fmac_f32_e32 v216, v177, v49
	v_add_f32_dpp v214, v214, v214 quad_perm:[2,3,0,1] row_mask:0xf bank_mask:0xf bound_ctrl:1
	v_fmac_f32_e32 v216, v195, v43
	v_fmac_f32_e32 v216, v197, v45
	v_add_f32_dpp v214, v214, v214 row_half_mirror row_mask:0xf bank_mask:0xf bound_ctrl:1
	v_fmac_f32_e32 v216, v191, v39
	v_fmac_f32_e32 v216, v193, v41
	v_add_f32_dpp v225, v214, v214 row_mirror row_mask:0xf bank_mask:0xf bound_ctrl:1
	v_fma_f32 v214, v182, v50, 0
	v_fmac_f32_e32 v214, v184, v52
	v_fmac_f32_e32 v214, v174, v46
	v_fmac_f32_e32 v214, v176, v48
	v_fmac_f32_e32 v214, v194, v42
	v_fmac_f32_e32 v214, v196, v44
	v_fmac_f32_e32 v214, v190, v38
	v_fmac_f32_e32 v214, v192, v40
	v_add_f32_e32 v214, v214, v216
	v_add_f32_dpp v213, v213, v213 quad_perm:[1,0,3,2] row_mask:0xf bank_mask:0xf bound_ctrl:1
	ds_bpermute_b32 v218, v200, v215
	v_add_f32_dpp v214, v214, v214 quad_perm:[1,0,3,2] row_mask:0xf bank_mask:0xf bound_ctrl:1
	v_add_f32_dpp v213, v213, v213 quad_perm:[2,3,0,1] row_mask:0xf bank_mask:0xf bound_ctrl:1
	ds_bpermute_b32 v220, v200, v217
	v_add_f32_dpp v214, v214, v214 quad_perm:[2,3,0,1] row_mask:0xf bank_mask:0xf bound_ctrl:1
	v_add_f32_dpp v213, v213, v213 row_half_mirror row_mask:0xf bank_mask:0xf bound_ctrl:1
	ds_bpermute_b32 v222, v200, v219
	v_add_f32_dpp v214, v214, v214 row_half_mirror row_mask:0xf bank_mask:0xf bound_ctrl:1
	v_add_f32_dpp v213, v213, v213 row_mirror row_mask:0xf bank_mask:0xf bound_ctrl:1
	ds_bpermute_b32 v216, v200, v213
	v_add_f32_dpp v227, v214, v214 row_mirror row_mask:0xf bank_mask:0xf bound_ctrl:1
	ds_bpermute_b32 v224, v200, v221
	ds_bpermute_b32 v226, v200, v223
	ds_bpermute_b32 v228, v200, v225
	ds_bpermute_b32 v229, v200, v227
	s_waitcnt lgkmcnt(4)
	v_add_f32_e32 v213, v213, v216
	v_add_f32_e32 v215, v215, v218
	v_add_f32_e32 v217, v217, v220
	v_add_f32_e32 v219, v219, v222
	s_waitcnt lgkmcnt(3)
	v_add_f32_e32 v221, v221, v224
	s_waitcnt lgkmcnt(2)
	v_add_f32_e32 v223, v223, v226
	s_waitcnt lgkmcnt(1)
	v_add_f32_e32 v225, v225, v228
	s_waitcnt lgkmcnt(0)
	v_add_f32_e32 v227, v227, v229
	ds_bpermute_b32 v214, v203, v213
	ds_bpermute_b32 v216, v203, v215
	ds_bpermute_b32 v218, v203, v217
	ds_bpermute_b32 v220, v203, v219
	ds_bpermute_b32 v222, v203, v221
	ds_bpermute_b32 v224, v203, v223
	ds_bpermute_b32 v226, v203, v225
	ds_bpermute_b32 v228, v203, v227
	s_and_saveexec_b64 s[14:15], s[2:3]
	s_cbranch_execz .LBB0_77
	s_waitcnt lgkmcnt(0)
	v_add_f32_e32 v227, v227, v228
	v_add_f32_e32 v225, v225, v226
	v_add_f32_e32 v226, v37, v227
	v_mul_f32_e64 v227, |v226|, s30
	v_exp_f32_e32 v227, v227
	v_add_f32_e32 v221, v221, v222
	v_add_f32_e32 v222, v219, v220
	v_add_f32_e32 v213, v213, v214
	v_add_f32_e32 v219, 1.0, v227
	v_cmp_gt_f32_e32 vcc, s31, v219
	v_add_f32_e32 v227, v215, v216
	v_add_f32_e32 v216, v36, v225
	v_cndmask_b32_e64 v220, 0, 32, vcc
	v_ldexp_f32 v219, v219, v220
	v_log_f32_e32 v219, v219
	v_mul_f32_e64 v215, |v216|, s30
	v_exp_f32_e32 v215, v215
	v_add_f32_e32 v223, v223, v224
	v_mul_f32_e32 v214, 0x3f317217, v219
	v_fma_f32 v214, v219, s33, -v214
	v_fmac_f32_e32 v214, 0x3377d1cf, v219
	v_fmac_f32_e32 v214, 0x3f317217, v219
	v_cmp_lt_f32_e64 s[4:5], |v219|, s34
	v_add_f32_e32 v215, 1.0, v215
	v_add_f32_e32 v224, v217, v218
	v_cndmask_b32_e64 v214, v219, v214, s[4:5]
	v_cmp_gt_f32_e64 s[4:5], s31, v215
	v_add_f32_e32 v220, v35, v223
	v_mul_f32_e64 v219, |v220|, s30
	v_cndmask_b32_e64 v217, 0, 32, s[4:5]
	v_ldexp_f32 v215, v215, v217
	v_log_f32_e32 v218, v215
	v_cndmask_b32_e32 v215, 0, v212, vcc
	v_sub_f32_e32 v215, v214, v215
	v_exp_f32_e32 v219, v219
	v_mul_f32_e32 v214, 0x3f317217, v218
	v_fma_f32 v214, v218, s33, -v214
	v_fmac_f32_e32 v214, 0x3377d1cf, v218
	v_fmac_f32_e32 v214, 0x3f317217, v218
	v_cmp_lt_f32_e64 vcc, |v218|, s34
	v_add_f32_e32 v223, v34, v221
	v_mul_f32_e64 v221, |v223|, s30
	v_cndmask_b32_e32 v214, v218, v214, vcc
	v_add_f32_e32 v218, 1.0, v219
	v_cmp_gt_f32_e32 vcc, s31, v218
	v_exp_f32_e32 v221, v221
	v_mul_f32_e32 v213, 0xbfb8aa3b, v213
	v_cndmask_b32_e64 v219, 0, 32, vcc
	v_ldexp_f32 v218, v218, v219
	v_log_f32_e32 v218, v218
	v_cndmask_b32_e64 v219, 0, v212, s[4:5]
	v_sub_f32_e32 v214, v214, v219
	v_exp_f32_e32 v213, v213
	v_mul_f32_e32 v219, 0x3f317217, v218
	v_fma_f32 v219, v218, s33, -v219
	v_fmac_f32_e32 v219, 0x3377d1cf, v218
	v_fmac_f32_e32 v219, 0x3f317217, v218
	v_cmp_lt_f32_e64 s[4:5], |v218|, s34
	v_mul_f32_e32 v222, 0xbfb8aa3b, v222
	v_max_f32_e32 v217, 0, v226
	v_cndmask_b32_e64 v218, v218, v219, s[4:5]
	v_add_f32_e32 v219, 1.0, v221
	v_cmp_gt_f32_e64 s[4:5], s31, v219
	v_max_f32_e32 v216, 0, v216
	v_exp_f32_e32 v222, v222
	v_cndmask_b32_e64 v221, 0, 32, s[4:5]
	v_ldexp_f32 v219, v219, v221
	v_log_f32_e32 v225, v219
	v_cndmask_b32_e32 v219, 0, v212, vcc
	v_sub_f32_e32 v219, v218, v219
	v_max_f32_e32 v221, 0, v220
	v_mul_f32_e32 v218, 0x3f317217, v225
	v_fma_f32 v218, v225, s33, -v218
	v_fmac_f32_e32 v218, 0x3377d1cf, v225
	v_fmac_f32_e32 v218, 0x3f317217, v225
	v_cmp_lt_f32_e64 vcc, |v225|, s34
	v_cndmask_b32_e64 v220, 0, v212, s[4:5]
	v_pk_add_f32 v[214:215], v[216:217], v[214:215]
	v_cndmask_b32_e32 v218, v225, v218, vcc
	v_sub_f32_e32 v218, v218, v220
	v_max_f32_e32 v220, 0, v223
	v_mul_f32_e32 v223, 0xbfb8aa3b, v224
	v_mul_f32_e32 v224, 0xbfb8aa3b, v227
	v_exp_f32_e32 v224, v224
	v_exp_f32_e32 v223, v223
	v_pk_add_f32 v[218:219], v[220:221], v[218:219]
	v_add_f32_e32 v213, 1.0, v213
	v_pk_mul_f32 v[216:217], v[214:215], s[10:11]
	v_pk_mul_f32 v[214:215], v[218:219], s[8:9] neg_lo:[0,1] neg_hi:[0,1]
	v_rcp_f32_e32 v218, v213
	v_add_f32_e32 v213, 1.0, v224
	v_rcp_f32_e32 v219, v213
	v_add_f32_e32 v213, 1.0, v223
	v_rcp_f32_e32 v220, v213
	v_add_f32_e32 v213, 1.0, v222
	s_lshl_b64 s[4:5], s[12:13], 4
	v_rcp_f32_e32 v221, v213
	s_add_u32 s12, s24, s4
	s_addc_u32 s13, s25, s5
	s_add_u32 s4, s26, s4
	s_addc_u32 s5, s27, s5
	global_store_dwordx4 v201, v[218:221], s[12:13] sc1
	global_store_dwordx4 v201, v[214:217], s[4:5] sc1
	s_branch .LBB0_77
